# attention: per-segment s_setprio flips removed, one static s_setprio 1 for waves 4..7 before the unit loop
# speedup vs baseline: 1.0037x; 1.0037x over previous
.LBB0_809:
	s_or_b64 exec, exec, s[0:1]
	s_mov_b64 s[0:1], s[92:93]
	s_waitcnt lgkmcnt(0)
	s_barrier
	s_load_dwordx2 s[12:13], s[0:1], 0xd8
	v_mov_b32_e32 v187, v230
	v_mov_b32_e32 v0, 0x3f80
	v_and_b32_e32 v189, 63, v187
	s_waitcnt lgkmcnt(0)
	s_add_u32 s0, s12, 0x186a0000
	s_addc_u32 s1, s13, 0
	v_writelane_b32 v252, s0, 12
	v_cmp_gt_u32_e64 s[6:7], 32, v189
	v_mov_b32_e32 v1, 0x5040100
	v_writelane_b32 v252, s1, 13
	s_add_u32 s0, s12, 0x32a0000
	s_addc_u32 s1, s13, 0
	v_writelane_b32 v252, s0, 14
	v_cndmask_b32_e64 v0, 0, v0, s[6:7]
	v_perm_b32 v129, 0, v0, v1
	v_writelane_b32 v252, s1, 15
	s_add_u32 s0, s12, 0x30a0000
	v_writelane_b32 v252, s0, 16
	s_addc_u32 s0, s13, 0
	v_writelane_b32 v252, s0, 17
	s_add_u32 s0, s12, 0x3ca0000
	v_writelane_b32 v252, s0, 18
	s_addc_u32 s0, s13, 0
	v_writelane_b32 v252, s0, 19
	s_add_u32 s0, s12, 0x3da0000
	v_writelane_b32 v252, s0, 20
	s_addc_u32 s0, s13, 0
	v_writelane_b32 v252, s0, 21
	s_add_u32 s0, s12, 0x106a0000
	s_addc_u32 s1, s13, 0
	v_writelane_b32 v252, s0, 22
	s_mov_b64 s[2:3], 0x8000
	v_cmp_eq_u32_e64 s[4:5], 0, v187
	v_writelane_b32 v252, s1, 23
	s_add_u32 s0, s12, 0x146a0000
	s_addc_u32 s1, s13, 0
	v_writelane_b32 v252, s0, 24
	v_bfe_u32 v3, v187, 5, 1
	v_and_b32_e32 v5, 7, v187
	v_writelane_b32 v252, s1, 25
	s_add_u32 s0, s12, 0x8000
	s_addc_u32 s1, s13, 0
	v_writelane_b32 v252, s0, 26
	v_lshlrev_b32_e32 v4, 3, v5
	v_lshlrev_b32_e32 v5, 4, v5
	v_writelane_b32 v252, s1, 27
	s_mov_b32 s0, 0x5040100
	v_perm_b32 v128, v0, v0, s0
	v_ashrrev_i32_e32 v0, 3, v187
	v_ashrrev_i32_e32 v1, 31, v0
	s_pack_ll_b32_b16 s0, 0, 0
	v_lshlrev_b64 v[198:199], 8, v[0:1]
	v_writelane_b32 v252, s4, 28
	v_mov_b32_e32 v130, s0
	v_mov_b32_e32 v131, s0
	s_movk_i32 s0, 0x1300
	v_lshl_add_u64 v[202:203], v[198:199], 0, s[2:3]
	s_mov_b64 s[2:3], 0xc000
	v_writelane_b32 v252, s5, 29
	v_mad_i64_i32 v[190:191], s[4:5], v0, s0, 0
	s_movk_i32 s0, 0x90
	v_lshl_add_u64 v[204:205], v[198:199], 0, s[2:3]
	v_cmp_ne_u32_e64 s[2:3], 0, v189
	v_mul_lo_u32 v8, v0, s0
	v_lshrrev_b32_e32 v6, 2, v187
	v_and_b32_e32 v7, 16, v187
	v_lshlrev_b32_e32 v196, 2, v3
	v_lshlrev_b32_e32 v234, 2, v189
	v_writelane_b32 v252, s2, 30
	v_lshlrev_b32_e32 v188, 3, v3
	v_add_u32_e32 v197, v8, v5
	v_lshlrev_b32_e32 v233, 4, v3
	v_and_or_b32 v3, v6, 3, v196
	v_and_or_b32 v6, v234, 12, v7
	v_writelane_b32 v252, s3, 31
	v_cmp_eq_u32_e64 s[2:3], 0, v189
	v_and_b32_e32 v193, 31, v187
	v_add_u32_e32 v192, 0, v197
	v_mul_u32_u24_e32 v3, 0xc0, v3
	v_lshlrev_b32_e32 v6, 1, v6
	v_writelane_b32 v252, s2, 32
	s_movk_i32 s70, 0x2600
	v_mad_u64_u32 v[194:195], s[4:5], v0, 48, v[192:193]
	v_add3_u32 v235, 0, v3, v6
	v_lshlrev_b64 v[6:7], 7, v[0:1]
	v_writelane_b32 v252, s3, 33
	v_mad_i64_i32 v[0:1], s[2:3], v0, s70, 0
	v_bfe_u32 v236, v187, 3, 3
	v_or_b32_e32 v0, v0, v5
	v_and_b32_e32 v237, 4, v236
	v_lshl_add_u64 v[0:1], s[12:13], 0, v[0:1]
	s_mov_b64 s[2:3], 0x186a0e00
	v_lshl_add_u64 v[206:207], v[0:1], 0, s[2:3]
	v_lshl_or_b32 v0, v193, 8, v237
	v_mad_u32_u24 v232, v193, s0, 0
	v_or_b32_e32 v6, v6, v4
	s_mov_b64 s[4:5], 0x4000
	v_add_u32_e32 v3, 0, v8
	v_add_u32_e32 v0, 0, v0
	s_mov_b32 s1, 0
	v_mov_b32_e32 v2, 0
	v_or_b32_e32 v190, v190, v4
	v_cmp_gt_i32_e64 s[8:9], 64, v187
	v_cmp_lt_i32_e64 s[10:11], 63, v187
	v_mul_lo_u32 v195, v187, s0
	v_add_u32_e32 v238, 0, v234
	v_add_u32_e32 v239, v232, v233
	v_lshl_add_u32 v240, v187, 3, 0
	v_lshl_add_u64 v[200:201], v[198:199], 0, s[4:5]
	v_lshl_add_u32 v241, v189, 3, 0
	v_add_u32_e32 v242, 0xb000, v0
	s_add_i32 s97, 0, 0x20080
	s_movk_i32 s3, 0xffe0
	s_mov_b32 s4, 0xffff
	s_mov_b32 s5, 0xff800000
	s_mov_b32 s14, 0x40c00000
	v_lshlrev_b32_e32 v208, 1, v4
	v_mov_b32_e32 v243, 0x98000
	v_mov_b32_e32 v244, 0xff800000
	v_mbcnt_hi_u32_b32 v231, -1, v220
	v_lshlrev_b64 v[210:211], 1, v[6:7]
	v_add_u32_e32 v245, v3, v5
	s_mov_b32 s15, 0
	v_writelane_b32 v252, s94, 34
	s_nop 1
	v_writelane_b32 v252, s95, 35
	v_readfirstlane_b32 s0, v230
	s_nop 0
	s_cmp_lt_u32 s0, 0x100
	s_cbranch_scc1 .Lprio_done
	s_setprio 1
.Lprio_done:
	s_branch .LBB0_811

.LBB0_833:
	s_lshl_b32 s2, s64, 1
	s_or_b32 s2, s2, 1
	s_mul_i32 s12, s2, 0x2400
	v_add_u32_e32 v0, s12, v232
	v_add_u32_e32 v1, v0, v233
	ds_read_b128 v[4:7], v1
	ds_read_b128 v[8:11], v1 offset:32
	ds_read_b128 v[12:15], v1 offset:4608
	ds_read_b128 v[96:99], v1 offset:4640
	ds_read_b128 v[100:103], v1 offset:64
	ds_read_b128 v[104:107], v1 offset:96
	ds_read_b128 v[108:111], v1 offset:4672
	ds_read_b128 v[148:151], v1 offset:4704
	ds_read_b128 v[152:155], v0 offset:128
	ds_read_b128 v[182:185], v0 offset:4736
	s_mulk_i32 s2, 0x3000
	s_waitcnt lgkmcnt(9)
	v_mfma_f32_32x32x16_bf16 v[64:79], v[4:7], v[112:115], v[48:63]
	s_waitcnt lgkmcnt(7)
	v_mfma_f32_32x32x16_bf16 v[80:95], v[12:15], v[112:115], v[48:63]
	v_mfma_f32_32x32x16_bf16 v[64:79], v[8:11], v[116:119], v[64:79]
	v_add_u32_e32 v0, s2, v235
	s_waitcnt lgkmcnt(6)
	v_mfma_f32_32x32x16_bf16 v[80:95], v[96:99], v[116:119], v[80:95]
	s_waitcnt lgkmcnt(5)
	v_mfma_f32_32x32x16_bf16 v[64:79], v[100:103], v[120:123], v[64:79]
	s_waitcnt lgkmcnt(3)
	v_mfma_f32_32x32x16_bf16 v[80:95], v[108:111], v[120:123], v[80:95]
	v_mfma_f32_32x32x16_bf16 v[64:79], v[104:107], v[124:127], v[64:79]
	s_waitcnt lgkmcnt(2)
	v_mfma_f32_32x32x16_bf16 v[80:95], v[148:151], v[124:127], v[80:95]
	ds_read_b64_tr_b16 v[4:5], v0 offset:36864
	ds_read_b64_tr_b16 v[6:7], v0 offset:38400
	ds_read_b64_tr_b16 v[10:11], v0 offset:38464
	ds_read_b64_tr_b16 v[8:9], v0 offset:36928
	ds_read_b64_tr_b16 v[12:13], v0 offset:39936
	ds_read_b64_tr_b16 v[14:15], v0 offset:41472
	ds_read_b64_tr_b16 v[150:151], v0 offset:41536
	ds_read_b64_tr_b16 v[148:149], v0 offset:40000
	s_waitcnt lgkmcnt(9)
	v_mfma_f32_32x32x16_bf16 v[64:79], v[152:155], v[128:131], v[64:79]
	ds_read_b64_tr_b16 v[152:153], v0 offset:43008
	ds_read_b64_tr_b16 v[154:155], v0 offset:44544
	ds_read_b64_tr_b16 v[158:159], v0 offset:44608
	ds_read_b64_tr_b16 v[156:157], v0 offset:43072
	ds_read_b64_tr_b16 v[160:161], v0 offset:46080
	ds_read_b64_tr_b16 v[162:163], v0 offset:47616
	ds_read_b64_tr_b16 v[166:167], v0 offset:47680
	ds_read_b64_tr_b16 v[164:165], v0 offset:46144
	s_waitcnt lgkmcnt(14)
	v_mfma_f32_32x32x16_bf16 v[80:95], v[182:185], v[128:131], v[80:95]
	s_cmp_lg_u32 s66, 0
	s_cselect_b64 s[12:13], -1, 0
	s_sub_i32 s2, s63, 64
	v_cmp_le_i32_e32 vcc, s2, v172
	s_and_b64 s[16:17], s[12:13], vcc
	s_cmp_eq_u64 s[16:17], exec
	s_cbranch_scc1 .LBB0_837
	v_add_u32_e32 v0, s63, v237
	v_add_u32_e32 v1, 0xffffff81, v0
	v_add_u32_e32 v3, 0xffffffa1, v0
	v_cmp_gt_i32_e64 s[16:17], s3, v1
	v_cmp_gt_i32_e64 s[18:19], v3, v172
	s_or_b64 s[16:17], s[16:17], s[18:19]
	v_cmp_le_i32_e32 vcc, v1, v172
	v_cndmask_b32_e64 v80, v80, v244, s[16:17]
	v_add_u32_e32 v3, 0xffffff82, v0
	v_cmp_lt_i32_e64 s[16:17], v1, v172
	v_add_u32_e32 v1, 0xffffffa2, v0
	v_cmp_gt_i32_e64 s[18:19], s3, v3
	v_cmp_gt_i32_e64 s[20:21], v1, v172
	s_or_b64 s[18:19], s[18:19], s[20:21]
	v_add_u32_e32 v1, 0xffffff83, v0
	v_cndmask_b32_e64 v81, v81, v244, s[18:19]
	v_cmp_le_i32_e64 s[18:19], v1, v172
	v_add_u32_e32 v3, 0xffffffa3, v0
	v_cmp_gt_i32_e64 s[20:21], s3, v1
	v_add_u32_e32 v1, s63, v236
	v_cmp_gt_i32_e64 s[22:23], v3, v172
	v_add_u32_e32 v1, 0xffffff81, v1
	s_or_b64 s[20:21], s[20:21], s[22:23]
	v_or_b32_e32 v3, 3, v1
	v_or_b32_e32 v96, 35, v1
	v_cndmask_b32_e64 v82, v82, v244, s[20:21]
	v_cmp_le_i32_e64 s[20:21], v3, v172
	v_cmp_gt_i32_e64 s[22:23], s3, v3
	v_cmp_gt_i32_e64 s[24:25], v96, v172
	v_add_u32_e32 v3, 0xffffff89, v0
	v_add_u32_e32 v96, 0xffffffa9, v0
	s_or_b64 s[22:23], s[22:23], s[24:25]
	v_cmp_gt_i32_e64 s[24:25], s3, v3
	v_cmp_gt_i32_e64 s[26:27], v96, v172
	v_cndmask_b32_e64 v83, v83, v244, s[22:23]
	v_cmp_le_i32_e64 s[22:23], v3, v172
	s_or_b64 s[24:25], s[24:25], s[26:27]
	v_add_u32_e32 v3, 0xffffff8a, v0
	v_add_u32_e32 v96, 0xffffffaa, v0
	v_cndmask_b32_e64 v84, v84, v244, s[24:25]
	v_cmp_le_i32_e64 s[24:25], v3, v172
	v_cmp_gt_i32_e64 s[26:27], s3, v3
	v_cmp_gt_i32_e64 s[28:29], v96, v172
	v_add_u32_e32 v3, 0xffffff8b, v0
	v_add_u32_e32 v96, 0xffffffab, v0
	s_or_b64 s[26:27], s[26:27], s[28:29]
	v_cmp_gt_i32_e64 s[28:29], s3, v3
	v_cmp_gt_i32_e64 s[30:31], v96, v172
	v_cndmask_b32_e64 v85, v85, v244, s[26:27]
	v_cmp_le_i32_e64 s[26:27], v3, v172
	s_or_b64 s[28:29], s[28:29], s[30:31]
	v_or_b32_e32 v3, 11, v1
	v_or_b32_e32 v96, 43, v1
	v_cndmask_b32_e64 v86, v86, v244, s[28:29]
	v_cmp_le_i32_e64 s[28:29], v3, v172
	v_cmp_gt_i32_e64 s[30:31], s3, v3
	v_cmp_gt_i32_e64 s[34:35], v96, v172
	v_add_u32_e32 v3, 0xffffff91, v0
	v_add_u32_e32 v96, 0xffffffb1, v0
	s_or_b64 s[30:31], s[30:31], s[34:35]
	v_cmp_gt_i32_e64 s[34:35], s3, v3
	v_cmp_gt_i32_e64 s[36:37], v96, v172
	v_cndmask_b32_e64 v87, v87, v244, s[30:31]
	v_cmp_le_i32_e64 s[30:31], v3, v172
	s_or_b64 s[34:35], s[34:35], s[36:37]
	v_add_u32_e32 v3, 0xffffff92, v0
	v_add_u32_e32 v96, 0xffffffb2, v0
	v_cndmask_b32_e64 v88, v88, v244, s[34:35]
	v_cmp_le_i32_e64 s[34:35], v3, v172
	v_cmp_gt_i32_e64 s[36:37], s3, v3
	v_cmp_gt_i32_e64 s[38:39], v96, v172
	v_add_u32_e32 v3, 0xffffff93, v0
	v_add_u32_e32 v96, 0xffffffb3, v0
	s_or_b64 s[36:37], s[36:37], s[38:39]
	v_cmp_gt_i32_e64 s[38:39], s3, v3
	v_cmp_gt_i32_e64 s[40:41], v96, v172
	v_cndmask_b32_e64 v89, v89, v244, s[36:37]
	v_cmp_le_i32_e64 s[36:37], v3, v172
	s_or_b64 s[38:39], s[38:39], s[40:41]
	v_or_b32_e32 v3, 19, v1
	v_or_b32_e32 v96, 51, v1
	v_cndmask_b32_e64 v90, v90, v244, s[38:39]
	v_cmp_le_i32_e64 s[38:39], v3, v172
	v_cmp_gt_i32_e64 s[40:41], s3, v3
	v_cmp_gt_i32_e64 s[42:43], v96, v172
	v_add_u32_e32 v3, 0xffffff99, v0
	v_add_u32_e32 v96, 0xffffffb9, v0
	s_or_b64 s[40:41], s[40:41], s[42:43]
	v_cmp_gt_i32_e64 s[42:43], s3, v3
	v_cmp_gt_i32_e64 s[44:45], v96, v172
	v_cndmask_b32_e64 v91, v91, v244, s[40:41]
	v_cmp_le_i32_e64 s[40:41], v3, v172
	s_or_b64 s[42:43], s[42:43], s[44:45]
	v_add_u32_e32 v3, 0xffffff9a, v0
	v_add_u32_e32 v96, 0xffffffba, v0
	v_cndmask_b32_e64 v92, v92, v244, s[42:43]
	v_cmp_le_i32_e64 s[42:43], v3, v172
	v_cmp_gt_i32_e64 s[44:45], s3, v3
	v_cmp_gt_i32_e64 s[46:47], v96, v172
	v_add_u32_e32 v3, 0xffffff9b, v0
	v_add_u32_e32 v0, 0xffffffbb, v0
	s_or_b64 s[44:45], s[44:45], s[46:47]
	v_cmp_gt_i32_e64 s[46:47], s3, v3
	v_cmp_gt_i32_e64 s[48:49], v0, v172
	v_or_b32_e32 v0, 27, v1
	v_or_b32_e32 v1, 59, v1
	s_or_b64 s[46:47], s[46:47], s[48:49]
	v_cmp_gt_i32_e64 s[48:49], s3, v0
	v_cmp_gt_i32_e64 s[50:51], v1, v172
	v_cndmask_b32_e64 v93, v93, v244, s[44:45]
	v_cmp_le_i32_e64 s[44:45], v3, v172
	v_cndmask_b32_e64 v94, v94, v244, s[46:47]
	v_cmp_le_i32_e64 s[46:47], v0, v172
	s_or_b64 s[50:51], s[48:49], s[50:51]
	s_and_saveexec_b64 s[48:49], s[50:51]
	v_mov_b32_e32 v95, s5
	s_or_b64 exec, exec, s[48:49]
	s_and_b64 vcc, s[12:13], vcc
	v_cndmask_b32_e32 v64, v244, v64, vcc
	s_and_b64 vcc, s[12:13], s[16:17]
	v_cndmask_b32_e32 v65, v244, v65, vcc
	s_and_b64 vcc, s[12:13], s[18:19]
	v_cndmask_b32_e32 v66, v244, v66, vcc
	s_and_b64 vcc, s[12:13], s[20:21]
	v_cndmask_b32_e32 v67, v244, v67, vcc
	s_and_b64 vcc, s[12:13], s[22:23]
	v_cndmask_b32_e32 v68, v244, v68, vcc
	s_and_b64 vcc, s[12:13], s[24:25]
	v_cndmask_b32_e32 v69, v244, v69, vcc
	s_and_b64 vcc, s[12:13], s[26:27]
	v_cndmask_b32_e32 v70, v244, v70, vcc
	s_and_b64 vcc, s[12:13], s[28:29]
	v_cndmask_b32_e32 v71, v244, v71, vcc
	s_and_b64 vcc, s[12:13], s[30:31]
	v_cndmask_b32_e32 v72, v244, v72, vcc
	s_and_b64 vcc, s[12:13], s[34:35]
	v_cndmask_b32_e32 v73, v244, v73, vcc
	s_and_b64 vcc, s[12:13], s[36:37]
	v_cndmask_b32_e32 v74, v244, v74, vcc
	s_and_b64 vcc, s[12:13], s[38:39]
	v_cndmask_b32_e32 v75, v244, v75, vcc
	s_and_b64 vcc, s[12:13], s[40:41]
	v_cndmask_b32_e32 v76, v244, v76, vcc
	s_and_b64 vcc, s[12:13], s[42:43]
	v_cndmask_b32_e32 v77, v244, v77, vcc
	s_and_b64 vcc, s[12:13], s[44:45]
	v_cndmask_b32_e32 v78, v244, v78, vcc
	s_and_b64 vcc, s[12:13], s[46:47]
	v_cndmask_b32_e32 v79, v244, v79, vcc

.LBB0_843:
	v_exp_f32_e32 v96, v64
	v_exp_f32_e32 v64, v80
	v_exp_f32_e32 v97, v65
	v_exp_f32_e32 v65, v81
	v_exp_f32_e32 v98, v66
	v_exp_f32_e32 v66, v82
	v_exp_f32_e32 v99, v67
	v_exp_f32_e32 v67, v83
	v_exp_f32_e32 v100, v68
	v_exp_f32_e32 v68, v84
	v_exp_f32_e32 v101, v69
	v_exp_f32_e32 v69, v85
	v_exp_f32_e32 v102, v70
	v_exp_f32_e32 v70, v86
	v_exp_f32_e32 v103, v71
	v_exp_f32_e32 v71, v87
	v_exp_f32_e32 v104, v72
	v_exp_f32_e32 v72, v88
	v_exp_f32_e32 v105, v73
	v_exp_f32_e32 v73, v89
	v_exp_f32_e32 v106, v74
	v_exp_f32_e32 v74, v90
	v_exp_f32_e32 v107, v75
	v_exp_f32_e32 v75, v91
	v_exp_f32_e32 v108, v76
	v_exp_f32_e32 v76, v92
	v_exp_f32_e32 v109, v77
	v_exp_f32_e32 v77, v93
	v_exp_f32_e32 v110, v78
	v_exp_f32_e32 v78, v94
	v_exp_f32_e32 v111, v79
	v_exp_f32_e32 v79, v95
	v_add_f32_e32 v0, v96, v64
	v_add_f32_e32 v1, v97, v65
	v_add_f32_e32 v3, v98, v66
	v_add_f32_e32 v80, v99, v67
	v_cvt_pk_bf16_f32 v81, v98, v99
	v_add_f32_e32 v0, v0, v100
	v_add_f32_e32 v1, v1, v101
	v_add_f32_e32 v3, v3, v102
	v_add_f32_e32 v80, v80, v103
	v_cvt_pk_bf16_f32 v82, v100, v101
	v_add_f32_e32 v0, v0, v68
	v_add_f32_e32 v1, v1, v69
	v_add_f32_e32 v3, v3, v70
	v_add_f32_e32 v80, v80, v71
	v_cvt_pk_bf16_f32 v83, v102, v103
	v_add_f32_e32 v0, v0, v104
	v_add_f32_e32 v1, v1, v105
	v_add_f32_e32 v3, v3, v106
	v_add_f32_e32 v80, v80, v107
	v_cvt_pk_bf16_f32 v84, v104, v105
	v_add_f32_e32 v0, v0, v72
	v_add_f32_e32 v1, v1, v73
	v_add_f32_e32 v3, v3, v74
	v_add_f32_e32 v80, v80, v75
	v_cvt_pk_bf16_f32 v85, v106, v107
	v_add_f32_e32 v0, v0, v108
	v_add_f32_e32 v1, v1, v109
	v_add_f32_e32 v3, v3, v110
	v_add_f32_e32 v80, v80, v111
	v_cvt_pk_bf16_f32 v86, v108, v109
	v_add_f32_e32 v0, v0, v76
	v_add_f32_e32 v1, v1, v77
	v_add_f32_e32 v3, v3, v78
	v_add_f32_e32 v80, v80, v79
	v_cvt_pk_bf16_f32 v87, v110, v111
	v_add_f32_e32 v0, v0, v1
	v_add_f32_e32 v1, v3, v80
	v_cvt_pk_bf16_f32 v80, v96, v97
	v_add_f32_e32 v0, v0, v1
	v_cvt_pk_bf16_f32 v64, v64, v65
	v_add_f32_e32 v180, v180, v0
	v_cvt_pk_bf16_f32 v65, v66, v67
	v_cvt_pk_bf16_f32 v66, v68, v69
	v_cvt_pk_bf16_f32 v67, v70, v71
	v_cvt_pk_bf16_f32 v68, v72, v73
	v_cvt_pk_bf16_f32 v69, v74, v75
	v_cvt_pk_bf16_f32 v70, v76, v77
	v_cvt_pk_bf16_f32 v71, v78, v79
	v_mfma_f32_32x32x16_bf16 v[32:47], v[4:7], v[80:83], v[32:47]
	s_waitcnt lgkmcnt(12)
	v_mfma_f32_32x32x16_bf16 v[16:31], v[8:11], v[80:83], v[16:31]
	s_waitcnt lgkmcnt(10)
	v_mfma_f32_32x32x16_bf16 v[32:47], v[12:15], v[84:87], v[32:47]
	s_waitcnt lgkmcnt(8)
	v_mfma_f32_32x32x16_bf16 v[16:31], v[148:151], v[84:87], v[16:31]
	s_waitcnt lgkmcnt(6)
	v_mfma_f32_32x32x16_bf16 v[32:47], v[152:155], v[64:67], v[32:47]
	s_waitcnt lgkmcnt(4)
	v_mfma_f32_32x32x16_bf16 v[16:31], v[156:159], v[64:67], v[16:31]
	s_waitcnt lgkmcnt(2)
	v_mfma_f32_32x32x16_bf16 v[32:47], v[160:163], v[68:71], v[32:47]
	s_waitcnt lgkmcnt(0)
	v_mfma_f32_32x32x16_bf16 v[16:31], v[164:167], v[68:71], v[16:31]
	s_andn2_b64 vcc, exec, s[56:57]
	s_mov_b64 s[12:13], -1
	s_cbranch_vccz .LBB0_858

.LBB0_846:
	s_mul_i32 s2, s64, 0x4800
	v_add_u32_e32 v0, s2, v232
	v_add_u32_e32 v1, v0, v233
	ds_read_b128 v[4:7], v1
	ds_read_b128 v[8:11], v1 offset:32
	ds_read_b128 v[12:15], v1 offset:4608
	ds_read_b128 v[96:99], v1 offset:4640
	ds_read_b128 v[100:103], v1 offset:64
	ds_read_b128 v[104:107], v1 offset:96
	ds_read_b128 v[108:111], v1 offset:4672
	ds_read_b128 v[148:151], v1 offset:4704
	ds_read_b128 v[152:155], v0 offset:128
	ds_read_b128 v[182:185], v0 offset:4736
	s_mul_i32 s2, s64, 0x6000
	s_waitcnt lgkmcnt(9)
	v_mfma_f32_32x32x16_bf16 v[64:79], v[4:7], v[112:115], v[48:63]
	s_waitcnt lgkmcnt(7)
	v_mfma_f32_32x32x16_bf16 v[80:95], v[12:15], v[112:115], v[48:63]
	v_mfma_f32_32x32x16_bf16 v[64:79], v[8:11], v[116:119], v[64:79]
	v_add_u32_e32 v0, s2, v235
	s_waitcnt lgkmcnt(6)
	v_mfma_f32_32x32x16_bf16 v[80:95], v[96:99], v[116:119], v[80:95]
	s_waitcnt lgkmcnt(5)
	v_mfma_f32_32x32x16_bf16 v[64:79], v[100:103], v[120:123], v[64:79]
	s_waitcnt lgkmcnt(3)
	v_mfma_f32_32x32x16_bf16 v[80:95], v[108:111], v[120:123], v[80:95]
	v_mfma_f32_32x32x16_bf16 v[64:79], v[104:107], v[124:127], v[64:79]
	s_waitcnt lgkmcnt(2)
	v_mfma_f32_32x32x16_bf16 v[80:95], v[148:151], v[124:127], v[80:95]
	ds_read_b64_tr_b16 v[4:5], v0 offset:36864
	ds_read_b64_tr_b16 v[6:7], v0 offset:38400
	ds_read_b64_tr_b16 v[10:11], v0 offset:38464
	ds_read_b64_tr_b16 v[8:9], v0 offset:36928
	ds_read_b64_tr_b16 v[12:13], v0 offset:39936
	ds_read_b64_tr_b16 v[14:15], v0 offset:41472
	ds_read_b64_tr_b16 v[150:151], v0 offset:41536
	ds_read_b64_tr_b16 v[148:149], v0 offset:40000
	s_waitcnt lgkmcnt(9)
	v_mfma_f32_32x32x16_bf16 v[64:79], v[152:155], v[128:131], v[64:79]
	ds_read_b64_tr_b16 v[152:153], v0 offset:43008
	ds_read_b64_tr_b16 v[154:155], v0 offset:44544
	ds_read_b64_tr_b16 v[158:159], v0 offset:44608
	ds_read_b64_tr_b16 v[156:157], v0 offset:43072
	ds_read_b64_tr_b16 v[160:161], v0 offset:46080
	ds_read_b64_tr_b16 v[162:163], v0 offset:47616
	ds_read_b64_tr_b16 v[166:167], v0 offset:47680
	ds_read_b64_tr_b16 v[164:165], v0 offset:46144
	s_waitcnt lgkmcnt(14)
	v_mfma_f32_32x32x16_bf16 v[80:95], v[182:185], v[128:131], v[80:95]
	v_cmp_le_i32_e32 vcc, s63, v172
	s_cmp_eq_u64 vcc, exec
	s_cbranch_scc1 .LBB0_850
	v_add_u32_e32 v0, s63, v237
	v_subrev_u32_e32 v3, 31, v0
	v_subrev_u32_e32 v1, 63, v0
	v_cmp_le_i32_e64 s[16:17], v3, v172
	v_cmp_le_i32_e32 vcc, v1, v172
	s_nop 3
	v_cndmask_b32_e64 v80, v244, v80, s[16:17]
	v_cmp_lt_i32_e64 s[16:17], v1, v172
	v_subrev_u32_e32 v1, 30, v0
	v_cmp_le_i32_e64 s[18:19], v1, v172
	v_subrev_u32_e32 v1, 61, v0
	s_nop 0
	v_cndmask_b32_e64 v81, v244, v81, s[18:19]
	v_cmp_le_i32_e64 s[18:19], v1, v172
	v_subrev_u32_e32 v1, 29, v0
	v_cmp_le_i32_e64 s[20:21], v1, v172
	v_add_u32_e32 v1, s63, v236
	v_subrev_u32_e32 v1, 63, v1
	v_or_b32_e32 v3, 3, v1
	v_cndmask_b32_e64 v82, v244, v82, s[20:21]
	v_cmp_le_i32_e64 s[20:21], v3, v172
	v_or_b32_e32 v3, 35, v1
	v_cmp_le_i32_e64 s[22:23], v3, v172
	v_subrev_u32_e32 v3, 55, v0
	s_nop 0
	v_cndmask_b32_e64 v83, v244, v83, s[22:23]
	v_cmp_le_i32_e64 s[22:23], v3, v172
	v_subrev_u32_e32 v3, 23, v0
	v_cmp_le_i32_e64 s[24:25], v3, v172
	v_subrev_u32_e32 v3, 54, v0
	s_nop 0
	v_cndmask_b32_e64 v84, v244, v84, s[24:25]
	v_cmp_le_i32_e64 s[24:25], v3, v172
	v_subrev_u32_e32 v3, 22, v0
	v_cmp_le_i32_e64 s[26:27], v3, v172
	v_subrev_u32_e32 v3, 53, v0
	s_nop 0
	v_cndmask_b32_e64 v85, v244, v85, s[26:27]
	v_cmp_le_i32_e64 s[26:27], v3, v172
	v_subrev_u32_e32 v3, 21, v0
	v_cmp_le_i32_e64 s[28:29], v3, v172
	v_or_b32_e32 v3, 11, v1
	s_nop 0
	v_cndmask_b32_e64 v86, v244, v86, s[28:29]
	v_cmp_le_i32_e64 s[28:29], v3, v172
	v_or_b32_e32 v3, 43, v1
	v_cmp_le_i32_e64 s[30:31], v3, v172
	v_subrev_u32_e32 v3, 47, v0
	s_nop 0
	v_cndmask_b32_e64 v87, v244, v87, s[30:31]
	v_cmp_le_i32_e64 s[30:31], v3, v172
	v_add_u32_e32 v3, -15, v0
	v_cmp_le_i32_e64 s[34:35], v3, v172
	v_subrev_u32_e32 v3, 46, v0
	s_nop 0
	v_cndmask_b32_e64 v88, v244, v88, s[34:35]
	v_cmp_le_i32_e64 s[34:35], v3, v172
	v_add_u32_e32 v3, -14, v0
	v_cmp_le_i32_e64 s[36:37], v3, v172
	v_subrev_u32_e32 v3, 45, v0
	s_nop 0
	v_cndmask_b32_e64 v89, v244, v89, s[36:37]
	v_cmp_le_i32_e64 s[36:37], v3, v172
	v_add_u32_e32 v3, -13, v0
	v_cmp_le_i32_e64 s[38:39], v3, v172
	v_or_b32_e32 v3, 19, v1
	s_nop 0
	v_cndmask_b32_e64 v90, v244, v90, s[38:39]
	v_cmp_le_i32_e64 s[38:39], v3, v172
	v_or_b32_e32 v3, 51, v1
	v_cmp_le_i32_e64 s[40:41], v3, v172
	v_subrev_u32_e32 v3, 39, v0
	s_nop 0
	v_cndmask_b32_e64 v91, v244, v91, s[40:41]
	v_cmp_le_i32_e64 s[40:41], v3, v172
	v_add_u32_e32 v3, -7, v0
	v_cmp_le_i32_e64 s[42:43], v3, v172
	v_subrev_u32_e32 v3, 38, v0
	s_nop 0
	v_cndmask_b32_e64 v92, v244, v92, s[42:43]
	v_cmp_le_i32_e64 s[42:43], v3, v172
	v_add_u32_e32 v3, -6, v0
	v_cmp_le_i32_e64 s[44:45], v3, v172
	v_subrev_u32_e32 v3, 37, v0
	v_add_u32_e32 v0, -5, v0
	v_cmp_le_i32_e64 s[46:47], v0, v172
	v_or_b32_e32 v0, 27, v1
	v_cndmask_b32_e64 v93, v244, v93, s[44:45]
	v_cndmask_b32_e64 v94, v244, v94, s[46:47]
	v_cmp_le_i32_e64 s[46:47], v0, v172
	v_or_b32_e32 v0, 59, v1
	v_cmp_le_i32_e64 s[44:45], v3, v172
	v_cmp_gt_i32_e64 s[48:49], v0, v172
	s_and_saveexec_b64 s[50:51], s[48:49]
	v_mov_b32_e32 v95, s5
	s_or_b64 exec, exec, s[50:51]
	v_cndmask_b32_e64 v65, v244, v65, s[16:17]
	v_cndmask_b32_e32 v64, v244, v64, vcc
	v_cndmask_b32_e64 v66, v244, v66, s[18:19]
	v_cndmask_b32_e64 v67, v244, v67, s[20:21]
	v_cndmask_b32_e64 v68, v244, v68, s[22:23]
	v_cndmask_b32_e64 v69, v244, v69, s[24:25]
	v_cndmask_b32_e64 v70, v244, v70, s[26:27]
	v_cndmask_b32_e64 v71, v244, v71, s[28:29]
	v_cndmask_b32_e64 v72, v244, v72, s[30:31]
	v_cndmask_b32_e64 v73, v244, v73, s[34:35]
	v_cndmask_b32_e64 v74, v244, v74, s[36:37]
	v_cndmask_b32_e64 v75, v244, v75, s[38:39]
	v_cndmask_b32_e64 v76, v244, v76, s[40:41]
	v_cndmask_b32_e64 v77, v244, v77, s[42:43]
	v_cndmask_b32_e64 v78, v244, v78, s[44:45]
	v_cndmask_b32_e64 v79, v244, v79, s[46:47]

.LBB0_856:
	v_exp_f32_e32 v96, v64
	v_exp_f32_e32 v64, v80
	v_exp_f32_e32 v97, v65
	v_exp_f32_e32 v65, v81
	v_exp_f32_e32 v98, v66
	v_exp_f32_e32 v66, v82
	v_exp_f32_e32 v99, v67
	v_exp_f32_e32 v67, v83
	v_exp_f32_e32 v100, v68
	v_exp_f32_e32 v68, v84
	v_exp_f32_e32 v101, v69
	v_exp_f32_e32 v69, v85
	v_exp_f32_e32 v102, v70
	v_exp_f32_e32 v70, v86
	v_exp_f32_e32 v103, v71
	v_exp_f32_e32 v71, v87
	v_exp_f32_e32 v104, v72
	v_exp_f32_e32 v72, v88
	v_exp_f32_e32 v105, v73
	v_exp_f32_e32 v73, v89
	v_exp_f32_e32 v106, v74
	v_exp_f32_e32 v74, v90
	v_exp_f32_e32 v107, v75
	v_exp_f32_e32 v75, v91
	v_exp_f32_e32 v108, v76
	v_exp_f32_e32 v76, v92
	v_exp_f32_e32 v109, v77
	v_exp_f32_e32 v77, v93
	v_exp_f32_e32 v110, v78
	v_exp_f32_e32 v78, v94
	v_exp_f32_e32 v111, v79
	v_exp_f32_e32 v79, v95
	v_add_f32_e32 v0, v96, v64
	v_add_f32_e32 v1, v97, v65
	v_add_f32_e32 v3, v98, v66
	v_add_f32_e32 v80, v99, v67
	v_cvt_pk_bf16_f32 v81, v98, v99
	v_add_f32_e32 v0, v0, v100
	v_add_f32_e32 v1, v1, v101
	v_add_f32_e32 v3, v3, v102
	v_add_f32_e32 v80, v80, v103
	v_cvt_pk_bf16_f32 v82, v100, v101
	v_add_f32_e32 v0, v0, v68
	v_add_f32_e32 v1, v1, v69
	v_add_f32_e32 v3, v3, v70
	v_add_f32_e32 v80, v80, v71
	v_cvt_pk_bf16_f32 v83, v102, v103
	v_add_f32_e32 v0, v0, v104
	v_add_f32_e32 v1, v1, v105
	v_add_f32_e32 v3, v3, v106
	v_add_f32_e32 v80, v80, v107
	v_cvt_pk_bf16_f32 v84, v104, v105
	v_add_f32_e32 v0, v0, v72
	v_add_f32_e32 v1, v1, v73
	v_add_f32_e32 v3, v3, v74
	v_add_f32_e32 v80, v80, v75
	v_cvt_pk_bf16_f32 v85, v106, v107
	v_add_f32_e32 v0, v0, v108
	v_add_f32_e32 v1, v1, v109
	v_add_f32_e32 v3, v3, v110
	v_add_f32_e32 v80, v80, v111
	v_cvt_pk_bf16_f32 v86, v108, v109
	v_add_f32_e32 v0, v0, v76
	v_add_f32_e32 v1, v1, v77
	v_add_f32_e32 v3, v3, v78
	v_add_f32_e32 v80, v80, v79
	v_cvt_pk_bf16_f32 v87, v110, v111
	v_add_f32_e32 v0, v0, v1
	v_add_f32_e32 v1, v3, v80
	v_cvt_pk_bf16_f32 v80, v96, v97
	v_add_f32_e32 v0, v0, v1
	v_cvt_pk_bf16_f32 v64, v64, v65
	v_add_f32_e32 v180, v180, v0
	v_cvt_pk_bf16_f32 v65, v66, v67
	v_cvt_pk_bf16_f32 v66, v68, v69
	v_cvt_pk_bf16_f32 v67, v70, v71
	v_cvt_pk_bf16_f32 v68, v72, v73
	v_cvt_pk_bf16_f32 v69, v74, v75
	v_cvt_pk_bf16_f32 v70, v76, v77
	v_cvt_pk_bf16_f32 v71, v78, v79
	v_mfma_f32_32x32x16_bf16 v[32:47], v[4:7], v[80:83], v[32:47]
	s_waitcnt lgkmcnt(12)
	v_mfma_f32_32x32x16_bf16 v[16:31], v[8:11], v[80:83], v[16:31]
	s_waitcnt lgkmcnt(10)
	v_mfma_f32_32x32x16_bf16 v[32:47], v[12:15], v[84:87], v[32:47]
	s_waitcnt lgkmcnt(8)
	v_mfma_f32_32x32x16_bf16 v[16:31], v[148:151], v[84:87], v[16:31]
	s_waitcnt lgkmcnt(6)
	v_mfma_f32_32x32x16_bf16 v[32:47], v[152:155], v[64:67], v[32:47]
	s_waitcnt lgkmcnt(4)
	v_mfma_f32_32x32x16_bf16 v[16:31], v[156:159], v[64:67], v[16:31]
	s_waitcnt lgkmcnt(2)
	v_mfma_f32_32x32x16_bf16 v[32:47], v[160:163], v[68:71], v[32:47]
	s_waitcnt lgkmcnt(0)
	v_mfma_f32_32x32x16_bf16 v[16:31], v[164:167], v[68:71], v[16:31]
	s_add_i32 s2, s63, 0xffffff81
	s_cmp_gt_i32 s2, s61
	s_cbranch_scc0 .LBB0_833

.LBB0_874:
	ds_read_b128 v[4:7], v239
	ds_read_b128 v[8:11], v239 offset:32
	ds_read_b128 v[12:15], v239 offset:4608
	ds_read_b128 v[48:51], v239 offset:4640
	ds_read_b128 v[52:55], v239 offset:64
	ds_read_b128 v[56:59], v239 offset:96
	ds_read_b128 v[60:63], v239 offset:4672
	ds_read_b128 v[112:115], v239 offset:4704
	s_lshl_b32 s0, s2, 6
	s_waitcnt lgkmcnt(7)
	v_mfma_f32_32x32x16_bf16 v[80:95], v[4:7], v[132:135], v[64:79]
	s_waitcnt lgkmcnt(5)
	v_mfma_f32_32x32x16_bf16 v[96:111], v[12:15], v[132:135], v[64:79]
	v_mfma_f32_32x32x16_bf16 v[80:95], v[8:11], v[136:139], v[80:95]
	ds_read_b64_tr_b16 v[4:5], v235 offset:18432
	ds_read_b64_tr_b16 v[6:7], v235 offset:19968
	ds_read_b64_tr_b16 v[10:11], v235 offset:20032
	ds_read_b64_tr_b16 v[8:9], v235 offset:18496
	ds_read_b64_tr_b16 v[12:13], v235 offset:21504
	ds_read_b64_tr_b16 v[14:15], v235 offset:23040
	ds_read_b64_tr_b16 v[166:167], v235 offset:23104
	ds_read_b64_tr_b16 v[164:165], v235 offset:21568
	ds_read_b64_tr_b16 v[168:169], v235 offset:24576
	ds_read_b64_tr_b16 v[170:171], v235 offset:26112
	ds_read_b64_tr_b16 v[174:175], v235 offset:26176
	ds_read_b64_tr_b16 v[172:173], v235 offset:24640
	ds_read_b64_tr_b16 v[176:177], v235 offset:27648
	ds_read_b64_tr_b16 v[178:179], v235 offset:29184
	ds_read_b64_tr_b16 v[182:183], v235 offset:29248
	ds_read_b64_tr_b16 v[180:181], v235 offset:27712
	s_waitcnt lgkmcnt(14)
	v_mfma_f32_32x32x16_bf16 v[96:111], v[48:51], v[136:139], v[96:111]
	v_mfma_f32_32x32x16_bf16 v[80:95], v[52:55], v[140:143], v[80:95]
	v_mfma_f32_32x32x16_bf16 v[96:111], v[60:63], v[140:143], v[96:111]
	v_mfma_f32_32x32x16_bf16 v[80:95], v[56:59], v[144:147], v[80:95]
	v_mfma_f32_32x32x16_bf16 v[96:111], v[112:115], v[144:147], v[96:111]
	s_or_b32 s2, s0, 63
	v_cmp_le_i32_e32 vcc, s2, v218
	s_cmp_eq_u64 vcc, exec
	s_cbranch_scc1 .LBB0_878
	v_or_b32_e32 v0, s0, v237
	v_or_b32_e32 v1, 32, v0
	v_cmp_le_i32_e64 s[16:17], v1, v218
	v_or_b32_e32 v1, 33, v0
	v_cmp_le_i32_e64 s[18:19], v1, v218
	v_or_b32_e32 v1, 2, v0
	v_cmp_le_i32_e32 vcc, v0, v218
	s_nop 0
	v_cndmask_b32_e64 v97, v244, v97, s[18:19]
	v_cmp_le_i32_e64 s[18:19], v1, v218
	v_or_b32_e32 v1, 34, v0
	v_cmp_le_i32_e64 s[20:21], v1, v218
	v_or_b32_e32 v1, s0, v236
	v_or_b32_e32 v3, 3, v1
	v_cndmask_b32_e64 v98, v244, v98, s[20:21]
	v_cmp_le_i32_e64 s[20:21], v3, v218
	v_or_b32_e32 v3, 35, v1
	v_cmp_le_i32_e64 s[22:23], v3, v218
	v_or_b32_e32 v3, 8, v0
	v_cndmask_b32_e64 v96, v244, v96, s[16:17]
	v_cndmask_b32_e64 v99, v244, v99, s[22:23]
	v_cmp_le_i32_e64 s[22:23], v3, v218
	v_or_b32_e32 v3, 40, v0
	v_cmp_le_i32_e64 s[24:25], v3, v218
	v_or_b32_e32 v3, 9, v0
	v_cmp_lt_i32_e64 s[16:17], v0, v218
	v_cndmask_b32_e64 v100, v244, v100, s[24:25]
	v_cmp_le_i32_e64 s[24:25], v3, v218
	v_or_b32_e32 v3, 41, v0
	v_cmp_le_i32_e64 s[26:27], v3, v218
	v_or_b32_e32 v3, 10, v0
	s_nop 0
	v_cndmask_b32_e64 v101, v244, v101, s[26:27]
	v_cmp_le_i32_e64 s[26:27], v3, v218
	v_or_b32_e32 v3, 42, v0
	v_cmp_le_i32_e64 s[28:29], v3, v218
	v_or_b32_e32 v3, 11, v1
	s_nop 0
	v_cndmask_b32_e64 v102, v244, v102, s[28:29]
	v_cmp_le_i32_e64 s[28:29], v3, v218
	v_or_b32_e32 v3, 43, v1
	v_cmp_le_i32_e64 s[30:31], v3, v218
	v_or_b32_e32 v3, 16, v0
	s_nop 0
	v_cndmask_b32_e64 v103, v244, v103, s[30:31]
	v_cmp_le_i32_e64 s[30:31], v3, v218
	v_or_b32_e32 v3, 48, v0
	v_cmp_le_i32_e64 s[34:35], v3, v218
	v_or_b32_e32 v3, 17, v0
	s_nop 0
	v_cndmask_b32_e64 v104, v244, v104, s[34:35]
	v_cmp_le_i32_e64 s[34:35], v3, v218
	v_or_b32_e32 v3, 49, v0
	v_cmp_le_i32_e64 s[36:37], v3, v218
	v_or_b32_e32 v3, 18, v0
	s_nop 0
	v_cndmask_b32_e64 v105, v244, v105, s[36:37]
	v_cmp_le_i32_e64 s[36:37], v3, v218
	v_or_b32_e32 v3, 50, v0
	v_cmp_le_i32_e64 s[38:39], v3, v218
	v_or_b32_e32 v3, 19, v1
	s_nop 0
	v_cndmask_b32_e64 v106, v244, v106, s[38:39]
	v_cmp_le_i32_e64 s[38:39], v3, v218
	v_or_b32_e32 v3, 51, v1
	v_cmp_le_i32_e64 s[40:41], v3, v218
	v_or_b32_e32 v3, 24, v0
	s_nop 0
	v_cndmask_b32_e64 v107, v244, v107, s[40:41]
	v_cmp_le_i32_e64 s[40:41], v3, v218
	v_or_b32_e32 v3, 56, v0
	v_cmp_le_i32_e64 s[42:43], v3, v218
	v_or_b32_e32 v3, 25, v0
	s_nop 0
	v_cndmask_b32_e64 v108, v244, v108, s[42:43]
	v_cmp_le_i32_e64 s[42:43], v3, v218
	v_or_b32_e32 v3, 57, v0
	v_cmp_le_i32_e64 s[44:45], v3, v218
	v_or_b32_e32 v3, 26, v0
	v_or_b32_e32 v0, 58, v0
	v_cmp_le_i32_e64 s[46:47], v0, v218
	v_or_b32_e32 v0, 27, v1
	v_cndmask_b32_e64 v109, v244, v109, s[44:45]
	v_cndmask_b32_e64 v110, v244, v110, s[46:47]
	v_cmp_le_i32_e64 s[46:47], v0, v218
	v_or_b32_e32 v0, 59, v1
	v_cmp_le_i32_e64 s[44:45], v3, v218
	v_cmp_gt_i32_e64 s[48:49], v0, v218
	s_and_saveexec_b64 s[58:59], s[48:49]
	v_mov_b32_e32 v111, s5
	s_or_b64 exec, exec, s[58:59]
	v_cndmask_b32_e64 v81, v244, v81, s[16:17]
	v_cndmask_b32_e32 v80, v244, v80, vcc
	v_cndmask_b32_e64 v82, v244, v82, s[18:19]
	v_cndmask_b32_e64 v83, v244, v83, s[20:21]
	v_cndmask_b32_e64 v84, v244, v84, s[22:23]
	v_cndmask_b32_e64 v85, v244, v85, s[24:25]
	v_cndmask_b32_e64 v86, v244, v86, s[26:27]
	v_cndmask_b32_e64 v87, v244, v87, s[28:29]
	v_cndmask_b32_e64 v88, v244, v88, s[30:31]
	v_cndmask_b32_e64 v89, v244, v89, s[34:35]
	v_cndmask_b32_e64 v90, v244, v90, s[36:37]
	v_cndmask_b32_e64 v91, v244, v91, s[38:39]
	v_cndmask_b32_e64 v92, v244, v92, s[40:41]
	v_cndmask_b32_e64 v93, v244, v93, s[42:43]
	v_cndmask_b32_e64 v94, v244, v94, s[44:45]
	v_cndmask_b32_e64 v95, v244, v95, s[46:47]

.LBB0_885:
	v_exp_f32_e32 v112, v80
	v_exp_f32_e32 v80, v96
	v_exp_f32_e32 v113, v81
	v_exp_f32_e32 v81, v97
	v_exp_f32_e32 v114, v82
	v_exp_f32_e32 v82, v98
	v_exp_f32_e32 v115, v83
	v_exp_f32_e32 v83, v99
	v_exp_f32_e32 v116, v84
	v_exp_f32_e32 v84, v100
	v_exp_f32_e32 v117, v85
	v_exp_f32_e32 v85, v101
	v_exp_f32_e32 v118, v86
	v_exp_f32_e32 v86, v102
	v_exp_f32_e32 v119, v87
	v_exp_f32_e32 v87, v103
	v_exp_f32_e32 v120, v88
	v_exp_f32_e32 v88, v104
	v_exp_f32_e32 v121, v89
	v_exp_f32_e32 v89, v105
	v_exp_f32_e32 v122, v90
	v_exp_f32_e32 v90, v106
	v_exp_f32_e32 v123, v91
	v_exp_f32_e32 v91, v107
	v_exp_f32_e32 v124, v92
	v_exp_f32_e32 v92, v108
	v_exp_f32_e32 v125, v93
	v_exp_f32_e32 v93, v109
	v_exp_f32_e32 v126, v94
	v_exp_f32_e32 v94, v110
	v_exp_f32_e32 v127, v95
	v_exp_f32_e32 v95, v111
	s_mov_b64 s[16:17], -1
	v_add_f32_e32 v0, v112, v80
	v_add_f32_e32 v1, v113, v81
	v_add_f32_e32 v3, v114, v82
	v_add_f32_e32 v96, v115, v83
	v_cvt_pk_bf16_f32 v97, v114, v115
	v_add_f32_e32 v0, v0, v116
	v_add_f32_e32 v1, v1, v117
	v_add_f32_e32 v3, v3, v118
	v_add_f32_e32 v96, v96, v119
	v_cvt_pk_bf16_f32 v98, v116, v117
	v_add_f32_e32 v0, v0, v84
	v_add_f32_e32 v1, v1, v85
	v_add_f32_e32 v3, v3, v86
	v_add_f32_e32 v96, v96, v87
	v_cvt_pk_bf16_f32 v99, v118, v119
	v_add_f32_e32 v0, v0, v120
	v_add_f32_e32 v1, v1, v121
	v_add_f32_e32 v3, v3, v122
	v_add_f32_e32 v96, v96, v123
	v_cvt_pk_bf16_f32 v100, v120, v121
	v_add_f32_e32 v0, v0, v88
	v_add_f32_e32 v1, v1, v89
	v_add_f32_e32 v3, v3, v90
	v_add_f32_e32 v96, v96, v91
	v_cvt_pk_bf16_f32 v101, v122, v123
	v_add_f32_e32 v0, v0, v124
	v_add_f32_e32 v1, v1, v125
	v_add_f32_e32 v3, v3, v126
	v_add_f32_e32 v96, v96, v127
	v_cvt_pk_bf16_f32 v102, v124, v125
	v_add_f32_e32 v0, v0, v92
	v_add_f32_e32 v1, v1, v93
	v_add_f32_e32 v3, v3, v94
	v_add_f32_e32 v96, v96, v95
	v_cvt_pk_bf16_f32 v103, v126, v127
	v_add_f32_e32 v0, v0, v1
	v_add_f32_e32 v1, v3, v96
	v_cvt_pk_bf16_f32 v96, v112, v113
	v_add_f32_e32 v0, v0, v1
	v_cvt_pk_bf16_f32 v80, v80, v81
	v_add_f32_e32 v209, v209, v0
	v_cvt_pk_bf16_f32 v81, v82, v83
	v_cvt_pk_bf16_f32 v82, v84, v85
	v_cvt_pk_bf16_f32 v83, v86, v87
	v_cvt_pk_bf16_f32 v84, v88, v89
	v_cvt_pk_bf16_f32 v85, v90, v91
	v_cvt_pk_bf16_f32 v86, v92, v93
	v_cvt_pk_bf16_f32 v87, v94, v95
	v_mfma_f32_32x32x16_bf16 v[32:47], v[4:7], v[96:99], v[32:47]
	s_waitcnt lgkmcnt(12)
	v_mfma_f32_32x32x16_bf16 v[16:31], v[8:11], v[96:99], v[16:31]
	s_waitcnt lgkmcnt(10)
	v_mfma_f32_32x32x16_bf16 v[32:47], v[12:15], v[100:103], v[32:47]
	s_waitcnt lgkmcnt(8)
	v_mfma_f32_32x32x16_bf16 v[16:31], v[164:167], v[100:103], v[16:31]
	s_waitcnt lgkmcnt(6)
	v_mfma_f32_32x32x16_bf16 v[32:47], v[168:171], v[80:83], v[32:47]
	s_waitcnt lgkmcnt(4)
	v_mfma_f32_32x32x16_bf16 v[16:31], v[172:175], v[80:83], v[16:31]
	s_waitcnt lgkmcnt(2)
	v_mfma_f32_32x32x16_bf16 v[32:47], v[176:179], v[84:87], v[32:47]
	s_waitcnt lgkmcnt(0)
	v_mfma_f32_32x32x16_bf16 v[16:31], v[180:183], v[84:87], v[16:31]
	s_cmp_lt_i32 s56, 0
	s_cbranch_scc1 .LBB0_900
	s_lshl_b64 s[16:17], 1, s69
	s_andn2_b64 s[58:59], s[12:13], s[16:17]
	s_ff1_i32_b64 s2, s[58:59]
	s_cmp_lg_u64 s[58:59], 0
	s_cselect_b32 s0, s2, -1
	s_cmp_lt_i32 s0, 0
	s_waitcnt vmcnt(1)
	ds_write_b128 v192, v[156:159] offset:9216
	s_waitcnt vmcnt(0)
	ds_write_b128 v194, v[160:163] offset:30720
	s_waitcnt lgkmcnt(0)
	s_barrier
	s_cbranch_scc1 .LBB0_888
	s_lshl_b64 s[12:13], s[0:1], 14
	v_lshl_add_u64 v[0:1], v[214:215], 0, s[12:13]
	v_lshl_add_u64 v[4:5], v[216:217], 0, s[12:13]
	global_load_dwordx4 v[156:159], v[0:1], off
	global_load_dwordx4 v[160:163], v[4:5], off
.LBB0_888:
	ds_read_b128 v[4:7], v239 offset:9216
	ds_read_b128 v[8:11], v239 offset:9248
	ds_read_b128 v[12:15], v239 offset:13824
	ds_read_b128 v[112:115], v239 offset:13856
	ds_read_b128 v[116:119], v239 offset:9280
	ds_read_b128 v[120:123], v239 offset:9312
	ds_read_b128 v[124:127], v239 offset:13888
	ds_read_b128 v[220:223], v239 offset:13920
	s_lshl_b32 s12, s56, 6
	s_waitcnt lgkmcnt(7)
	v_mfma_f32_32x32x16_bf16 v[80:95], v[4:7], v[132:135], v[48:63]
	s_waitcnt lgkmcnt(5)
	v_mfma_f32_32x32x16_bf16 v[96:111], v[12:15], v[132:135], v[48:63]
	v_mfma_f32_32x32x16_bf16 v[80:95], v[8:11], v[136:139], v[80:95]
	ds_read_b64_tr_b16 v[4:5], v235 offset:30720
	ds_read_b64_tr_b16 v[6:7], v235 offset:32256
	ds_read_b64_tr_b16 v[10:11], v235 offset:32320
	ds_read_b64_tr_b16 v[8:9], v235 offset:30784
	ds_read_b64_tr_b16 v[12:13], v235 offset:33792
	ds_read_b64_tr_b16 v[14:15], v235 offset:35328
	ds_read_b64_tr_b16 v[166:167], v235 offset:35392
	ds_read_b64_tr_b16 v[164:165], v235 offset:33856
	ds_read_b64_tr_b16 v[168:169], v235 offset:36864
	ds_read_b64_tr_b16 v[170:171], v235 offset:38400
	ds_read_b64_tr_b16 v[174:175], v235 offset:38464
	ds_read_b64_tr_b16 v[172:173], v235 offset:36928
	ds_read_b64_tr_b16 v[176:177], v235 offset:39936
	ds_read_b64_tr_b16 v[178:179], v235 offset:41472
	ds_read_b64_tr_b16 v[182:183], v235 offset:41536
	ds_read_b64_tr_b16 v[180:181], v235 offset:40000
	s_waitcnt lgkmcnt(14)
	v_mfma_f32_32x32x16_bf16 v[96:111], v[112:115], v[136:139], v[96:111]
	v_mfma_f32_32x32x16_bf16 v[80:95], v[116:119], v[140:143], v[80:95]
	v_mfma_f32_32x32x16_bf16 v[96:111], v[124:127], v[140:143], v[96:111]
	v_mfma_f32_32x32x16_bf16 v[80:95], v[120:123], v[144:147], v[80:95]
	v_mfma_f32_32x32x16_bf16 v[96:111], v[220:223], v[144:147], v[96:111]
	s_or_b32 s13, s12, 63
	v_cmp_le_i32_e32 vcc, s13, v218
	s_cmp_eq_u64 vcc, exec
	s_cbranch_scc1 .LBB0_892
	v_or_b32_e32 v0, s12, v237
	v_or_b32_e32 v1, 32, v0
	v_cmp_le_i32_e64 s[16:17], v1, v218
	v_or_b32_e32 v1, 33, v0
	v_cmp_le_i32_e64 s[18:19], v1, v218
	v_or_b32_e32 v1, 2, v0
	v_cmp_le_i32_e32 vcc, v0, v218
	s_nop 0
	v_cndmask_b32_e64 v97, v244, v97, s[18:19]
	v_cmp_le_i32_e64 s[18:19], v1, v218
	v_or_b32_e32 v1, 34, v0
	v_cmp_le_i32_e64 s[20:21], v1, v218
	v_or_b32_e32 v1, s12, v236
	v_or_b32_e32 v3, 3, v1
	v_cndmask_b32_e64 v98, v244, v98, s[20:21]
	v_cmp_le_i32_e64 s[20:21], v3, v218
	v_or_b32_e32 v3, 35, v1
	v_cmp_le_i32_e64 s[22:23], v3, v218
	v_or_b32_e32 v3, 8, v0
	v_cndmask_b32_e64 v96, v244, v96, s[16:17]
	v_cndmask_b32_e64 v99, v244, v99, s[22:23]
	v_cmp_le_i32_e64 s[22:23], v3, v218
	v_or_b32_e32 v3, 40, v0
	v_cmp_le_i32_e64 s[24:25], v3, v218
	v_or_b32_e32 v3, 9, v0
	v_cmp_lt_i32_e64 s[16:17], v0, v218
	v_cndmask_b32_e64 v100, v244, v100, s[24:25]
	v_cmp_le_i32_e64 s[24:25], v3, v218
	v_or_b32_e32 v3, 41, v0
	v_cmp_le_i32_e64 s[26:27], v3, v218
	v_or_b32_e32 v3, 10, v0
	s_nop 0
	v_cndmask_b32_e64 v101, v244, v101, s[26:27]
	v_cmp_le_i32_e64 s[26:27], v3, v218
	v_or_b32_e32 v3, 42, v0
	v_cmp_le_i32_e64 s[28:29], v3, v218
	v_or_b32_e32 v3, 11, v1
	s_nop 0
	v_cndmask_b32_e64 v102, v244, v102, s[28:29]
	v_cmp_le_i32_e64 s[28:29], v3, v218
	v_or_b32_e32 v3, 43, v1
	v_cmp_le_i32_e64 s[30:31], v3, v218
	v_or_b32_e32 v3, 16, v0
	s_nop 0
	v_cndmask_b32_e64 v103, v244, v103, s[30:31]
	v_cmp_le_i32_e64 s[30:31], v3, v218
	v_or_b32_e32 v3, 48, v0
	v_cmp_le_i32_e64 s[34:35], v3, v218
	v_or_b32_e32 v3, 17, v0
	s_nop 0
	v_cndmask_b32_e64 v104, v244, v104, s[34:35]
	v_cmp_le_i32_e64 s[34:35], v3, v218
	v_or_b32_e32 v3, 49, v0
	v_cmp_le_i32_e64 s[36:37], v3, v218
	v_or_b32_e32 v3, 18, v0
	s_nop 0
	v_cndmask_b32_e64 v105, v244, v105, s[36:37]
	v_cmp_le_i32_e64 s[36:37], v3, v218
	v_or_b32_e32 v3, 50, v0
	v_cmp_le_i32_e64 s[38:39], v3, v218
	v_or_b32_e32 v3, 19, v1
	s_nop 0
	v_cndmask_b32_e64 v106, v244, v106, s[38:39]
	v_cmp_le_i32_e64 s[38:39], v3, v218
	v_or_b32_e32 v3, 51, v1
	v_cmp_le_i32_e64 s[40:41], v3, v218
	v_or_b32_e32 v3, 24, v0
	s_nop 0
	v_cndmask_b32_e64 v107, v244, v107, s[40:41]
	v_cmp_le_i32_e64 s[40:41], v3, v218
	v_or_b32_e32 v3, 56, v0
	v_cmp_le_i32_e64 s[42:43], v3, v218
	v_or_b32_e32 v3, 25, v0
	s_nop 0
	v_cndmask_b32_e64 v108, v244, v108, s[42:43]
	v_cmp_le_i32_e64 s[42:43], v3, v218
	v_or_b32_e32 v3, 57, v0
	v_cmp_le_i32_e64 s[44:45], v3, v218
	v_or_b32_e32 v3, 26, v0
	v_or_b32_e32 v0, 58, v0
	v_cmp_le_i32_e64 s[46:47], v0, v218
	v_or_b32_e32 v0, 27, v1
	v_cndmask_b32_e64 v109, v244, v109, s[44:45]
	v_cndmask_b32_e64 v110, v244, v110, s[46:47]
	v_cmp_le_i32_e64 s[46:47], v0, v218
	v_or_b32_e32 v0, 59, v1
	v_cmp_le_i32_e64 s[44:45], v3, v218
	v_cmp_gt_i32_e64 s[48:49], v0, v218
	s_and_saveexec_b64 s[12:13], s[48:49]
	v_mov_b32_e32 v111, s5
	s_or_b64 exec, exec, s[12:13]
	v_cndmask_b32_e64 v81, v244, v81, s[16:17]
	v_cndmask_b32_e32 v80, v244, v80, vcc
	v_cndmask_b32_e64 v82, v244, v82, s[18:19]
	v_cndmask_b32_e64 v83, v244, v83, s[20:21]
	v_cndmask_b32_e64 v84, v244, v84, s[22:23]
	v_cndmask_b32_e64 v85, v244, v85, s[24:25]
	v_cndmask_b32_e64 v86, v244, v86, s[26:27]
	v_cndmask_b32_e64 v87, v244, v87, s[28:29]
	v_cndmask_b32_e64 v88, v244, v88, s[30:31]
	v_cndmask_b32_e64 v89, v244, v89, s[34:35]
	v_cndmask_b32_e64 v90, v244, v90, s[36:37]
	v_cndmask_b32_e64 v91, v244, v91, s[38:39]
	v_cndmask_b32_e64 v92, v244, v92, s[40:41]
	v_cndmask_b32_e64 v93, v244, v93, s[42:43]
	v_cndmask_b32_e64 v94, v244, v94, s[44:45]
	v_cndmask_b32_e64 v95, v244, v95, s[46:47]

.LBB0_898:
	v_exp_f32_e32 v112, v80
	v_exp_f32_e32 v80, v96
	v_exp_f32_e32 v113, v81
	v_exp_f32_e32 v81, v97
	v_exp_f32_e32 v114, v82
	v_exp_f32_e32 v82, v98
	v_exp_f32_e32 v115, v83
	v_exp_f32_e32 v83, v99
	v_exp_f32_e32 v116, v84
	v_exp_f32_e32 v84, v100
	v_exp_f32_e32 v117, v85
	v_exp_f32_e32 v85, v101
	v_exp_f32_e32 v118, v86
	v_exp_f32_e32 v86, v102
	v_exp_f32_e32 v119, v87
	v_exp_f32_e32 v87, v103
	v_exp_f32_e32 v120, v88
	v_exp_f32_e32 v88, v104
	v_exp_f32_e32 v121, v89
	v_exp_f32_e32 v89, v105
	v_exp_f32_e32 v122, v90
	v_exp_f32_e32 v90, v106
	v_exp_f32_e32 v123, v91
	v_exp_f32_e32 v91, v107
	v_exp_f32_e32 v124, v92
	v_exp_f32_e32 v92, v108
	v_exp_f32_e32 v125, v93
	v_exp_f32_e32 v93, v109
	v_exp_f32_e32 v126, v94
	v_exp_f32_e32 v94, v110
	v_exp_f32_e32 v127, v95
	v_exp_f32_e32 v95, v111
	v_add_f32_e32 v0, v112, v80
	v_add_f32_e32 v1, v113, v81
	v_add_f32_e32 v96, v115, v83
	v_add_f32_e32 v3, v114, v82
	v_cvt_pk_bf16_f32 v97, v114, v115
	v_add_f32_e32 v0, v0, v116
	v_add_f32_e32 v1, v1, v117
	v_add_f32_e32 v96, v96, v119
	v_add_f32_e32 v3, v3, v118
	v_cvt_pk_bf16_f32 v98, v116, v117
	v_add_f32_e32 v0, v0, v84
	v_add_f32_e32 v1, v1, v85
	v_add_f32_e32 v96, v96, v87
	v_add_f32_e32 v3, v3, v86
	v_cvt_pk_bf16_f32 v99, v118, v119
	v_add_f32_e32 v0, v0, v120
	v_add_f32_e32 v1, v1, v121
	v_add_f32_e32 v96, v96, v123
	v_add_f32_e32 v3, v3, v122
	v_cvt_pk_bf16_f32 v100, v120, v121
	v_add_f32_e32 v0, v0, v88
	v_add_f32_e32 v1, v1, v89
	v_add_f32_e32 v96, v96, v91
	v_add_f32_e32 v3, v3, v90
	v_cvt_pk_bf16_f32 v101, v122, v123
	v_add_f32_e32 v0, v0, v124
	v_add_f32_e32 v1, v1, v125
	v_add_f32_e32 v96, v96, v127
	v_add_f32_e32 v3, v3, v126
	v_cvt_pk_bf16_f32 v102, v124, v125
	v_add_f32_e32 v0, v0, v92
	v_add_f32_e32 v1, v1, v93
	v_add_f32_e32 v96, v96, v95
	v_add_f32_e32 v3, v3, v94
	v_cvt_pk_bf16_f32 v103, v126, v127
	v_add_f32_e32 v0, v0, v1
	v_add_f32_e32 v1, v3, v96
	v_cvt_pk_bf16_f32 v96, v112, v113
	v_add_f32_e32 v0, v0, v1
	v_cvt_pk_bf16_f32 v80, v80, v81
	v_cvt_pk_bf16_f32 v81, v82, v83
	v_cvt_pk_bf16_f32 v82, v84, v85
	v_cvt_pk_bf16_f32 v83, v86, v87
	v_cvt_pk_bf16_f32 v84, v88, v89
	v_cvt_pk_bf16_f32 v85, v90, v91
	v_cvt_pk_bf16_f32 v86, v92, v93
	v_cvt_pk_bf16_f32 v87, v94, v95
	v_mfma_f32_32x32x16_bf16 v[32:47], v[4:7], v[96:99], v[32:47]
	s_waitcnt lgkmcnt(12)
	v_mfma_f32_32x32x16_bf16 v[16:31], v[8:11], v[96:99], v[16:31]
	s_waitcnt lgkmcnt(10)
	v_mfma_f32_32x32x16_bf16 v[32:47], v[12:15], v[100:103], v[32:47]
	s_waitcnt lgkmcnt(8)
	v_mfma_f32_32x32x16_bf16 v[16:31], v[164:167], v[100:103], v[16:31]
	s_waitcnt lgkmcnt(6)
	v_mfma_f32_32x32x16_bf16 v[32:47], v[168:171], v[80:83], v[32:47]
	s_waitcnt lgkmcnt(4)
	v_mfma_f32_32x32x16_bf16 v[16:31], v[172:175], v[80:83], v[16:31]
	s_waitcnt lgkmcnt(2)
	v_mfma_f32_32x32x16_bf16 v[32:47], v[176:179], v[84:87], v[32:47]
	s_waitcnt lgkmcnt(0)
	v_mfma_f32_32x32x16_bf16 v[16:31], v[180:183], v[84:87], v[16:31]
	s_andn2_b64 vcc, exec, s[54:55]
	s_mov_b64 s[16:17], -1
	s_cbranch_vccnz .LBB0_871
	s_lshl_b64 s[12:13], 1, s2
	s_andn2_b64 s[12:13], s[58:59], s[12:13]
	s_mov_b64 s[16:17], 0
	s_waitcnt vmcnt(1)
	ds_write_b128 v192, v[148:151]
	s_waitcnt vmcnt(0)
	ds_write_b128 v194, v[152:155] offset:18432
	s_waitcnt lgkmcnt(0)
	s_barrier
	s_branch .LBB0_871

.LBB0_953:
	ds_read_b128 v[4:7], v239
	ds_read_b128 v[8:11], v239 offset:32
	ds_read_b128 v[12:15], v239 offset:4608
	ds_read_b128 v[96:99], v239 offset:4640
	ds_read_b128 v[100:103], v239 offset:64
	ds_read_b128 v[104:107], v239 offset:96
	ds_read_b128 v[108:111], v239 offset:4672
	ds_read_b128 v[112:115], v239 offset:4704
	v_lshrrev_b64 v[0:1], s2, v[214:215]
	v_and_b32_e32 v0, 1, v0
	s_lshl_b32 s26, s2, 6
	v_cmp_eq_u32_e64 s[16:17], 1, v0
	s_waitcnt lgkmcnt(7)
	v_mfma_f32_32x32x16_bf16 v[64:79], v[4:7], v[132:135], v[48:63]
	s_waitcnt lgkmcnt(5)
	v_mfma_f32_32x32x16_bf16 v[80:95], v[12:15], v[132:135], v[48:63]
	v_mfma_f32_32x32x16_bf16 v[64:79], v[8:11], v[136:139], v[64:79]
	ds_read_b64_tr_b16 v[4:5], v235 offset:18432
	ds_read_b64_tr_b16 v[6:7], v235 offset:19968
	ds_read_b64_tr_b16 v[10:11], v235 offset:20032
	ds_read_b64_tr_b16 v[8:9], v235 offset:18496
	ds_read_b64_tr_b16 v[12:13], v235 offset:21504
	ds_read_b64_tr_b16 v[14:15], v235 offset:23040
	ds_read_b64_tr_b16 v[166:167], v235 offset:23104
	ds_read_b64_tr_b16 v[164:165], v235 offset:21568
	ds_read_b64_tr_b16 v[168:169], v235 offset:24576
	ds_read_b64_tr_b16 v[170:171], v235 offset:26112
	ds_read_b64_tr_b16 v[174:175], v235 offset:26176
	ds_read_b64_tr_b16 v[172:173], v235 offset:24640
	ds_read_b64_tr_b16 v[176:177], v235 offset:27648
	ds_read_b64_tr_b16 v[178:179], v235 offset:29184
	ds_read_b64_tr_b16 v[182:183], v235 offset:29248
	ds_read_b64_tr_b16 v[180:181], v235 offset:27712
	s_waitcnt lgkmcnt(14)
	v_mfma_f32_32x32x16_bf16 v[80:95], v[96:99], v[136:139], v[80:95]
	v_mfma_f32_32x32x16_bf16 v[64:79], v[100:103], v[140:143], v[64:79]
	v_mfma_f32_32x32x16_bf16 v[80:95], v[108:111], v[140:143], v[80:95]
	v_mfma_f32_32x32x16_bf16 v[64:79], v[104:107], v[144:147], v[64:79]
	v_mfma_f32_32x32x16_bf16 v[80:95], v[112:115], v[144:147], v[80:95]
	s_or_b32 s2, s26, 63
	v_cmp_le_u32_e32 vcc, s2, v246
	s_cmp_eq_u64 vcc, exec
	s_cbranch_scc1 .LBB0_956
	v_or_b32_e32 v0, s26, v237
	v_cmp_le_u32_e32 vcc, v0, v246
	s_and_b64 vcc, s[16:17], vcc
	v_or_b32_e32 v1, 32, v0
	s_nop 2
	v_cndmask_b32_e32 v96, v244, v64, vcc
	v_cmp_le_u32_e32 vcc, v1, v246
	s_and_b64 vcc, s[16:17], vcc
	v_or_b32_e32 v1, 33, v0
	v_cndmask_b32_e32 v112, v244, v80, vcc
	v_cmp_lt_u32_e32 vcc, v0, v246
	s_and_b64 vcc, s[16:17], vcc
	s_xor_b64 s[12:13], s[16:17], -1
	v_cndmask_b32_e32 v97, v244, v65, vcc
	v_cmp_le_u32_e32 vcc, v1, v246
	s_and_b64 vcc, s[16:17], vcc
	v_or_b32_e32 v1, 2, v0
	v_cndmask_b32_e32 v113, v244, v81, vcc
	v_cmp_le_u32_e32 vcc, v1, v246
	s_and_b64 vcc, s[16:17], vcc
	v_or_b32_e32 v1, 34, v0
	v_cndmask_b32_e32 v98, v244, v66, vcc
	v_cmp_le_u32_e32 vcc, v1, v246
	v_or_b32_e32 v1, s26, v236
	s_and_b64 vcc, s[16:17], vcc
	v_or_b32_e32 v3, 3, v1
	v_cndmask_b32_e32 v114, v244, v82, vcc
	v_cmp_le_u32_e32 vcc, v3, v246
	s_and_b64 vcc, s[16:17], vcc
	v_or_b32_e32 v3, 35, v1
	v_cndmask_b32_e32 v99, v244, v67, vcc
	v_cmp_le_u32_e32 vcc, v3, v246
	s_and_b64 vcc, s[16:17], vcc
	v_or_b32_e32 v3, 8, v0
	v_cndmask_b32_e32 v115, v244, v83, vcc
	v_cmp_le_u32_e32 vcc, v3, v246
	s_and_b64 vcc, s[16:17], vcc
	v_or_b32_e32 v3, 40, v0
	v_cndmask_b32_e32 v100, v244, v68, vcc
	v_cmp_le_u32_e32 vcc, v3, v246
	s_and_b64 vcc, s[16:17], vcc
	v_or_b32_e32 v3, 9, v0
	v_cndmask_b32_e32 v116, v244, v84, vcc
	v_cmp_le_u32_e32 vcc, v3, v246
	s_and_b64 vcc, s[16:17], vcc
	v_or_b32_e32 v3, 41, v0
	v_cndmask_b32_e32 v101, v244, v69, vcc
	v_cmp_le_u32_e32 vcc, v3, v246
	s_and_b64 vcc, s[16:17], vcc
	v_or_b32_e32 v3, 10, v0
	v_cndmask_b32_e32 v117, v244, v85, vcc
	v_cmp_le_u32_e32 vcc, v3, v246
	s_and_b64 vcc, s[16:17], vcc
	v_or_b32_e32 v3, 42, v0
	v_cndmask_b32_e32 v102, v244, v70, vcc
	v_cmp_le_u32_e32 vcc, v3, v246
	s_and_b64 vcc, s[16:17], vcc
	v_or_b32_e32 v3, 11, v1
	v_cndmask_b32_e32 v118, v244, v86, vcc
	v_cmp_le_u32_e32 vcc, v3, v246
	s_and_b64 vcc, s[16:17], vcc
	v_or_b32_e32 v3, 43, v1
	v_cndmask_b32_e32 v103, v244, v71, vcc
	v_cmp_le_u32_e32 vcc, v3, v246
	s_and_b64 vcc, s[16:17], vcc
	v_or_b32_e32 v3, 16, v0
	v_cndmask_b32_e32 v119, v244, v87, vcc
	v_cmp_le_u32_e32 vcc, v3, v246
	s_and_b64 vcc, s[16:17], vcc
	v_or_b32_e32 v3, 48, v0
	v_cndmask_b32_e32 v104, v244, v72, vcc
	v_cmp_le_u32_e32 vcc, v3, v246
	s_and_b64 vcc, s[16:17], vcc
	v_or_b32_e32 v3, 17, v0
	v_cndmask_b32_e32 v120, v244, v88, vcc
	v_cmp_le_u32_e32 vcc, v3, v246
	s_and_b64 vcc, s[16:17], vcc
	v_or_b32_e32 v3, 49, v0
	v_cndmask_b32_e32 v105, v244, v73, vcc
	v_cmp_le_u32_e32 vcc, v3, v246
	s_and_b64 vcc, s[16:17], vcc
	v_or_b32_e32 v3, 18, v0
	v_cndmask_b32_e32 v121, v244, v89, vcc
	v_cmp_le_u32_e32 vcc, v3, v246
	s_and_b64 vcc, s[16:17], vcc
	v_or_b32_e32 v3, 50, v0
	v_cndmask_b32_e32 v106, v244, v74, vcc
	v_cmp_le_u32_e32 vcc, v3, v246
	s_and_b64 vcc, s[16:17], vcc
	v_or_b32_e32 v3, 19, v1
	v_cndmask_b32_e32 v122, v244, v90, vcc
	v_cmp_le_u32_e32 vcc, v3, v246
	s_and_b64 vcc, s[16:17], vcc
	v_or_b32_e32 v3, 51, v1
	v_cndmask_b32_e32 v107, v244, v75, vcc
	v_cmp_le_u32_e32 vcc, v3, v246
	s_and_b64 vcc, s[16:17], vcc
	v_or_b32_e32 v3, 24, v0
	v_cndmask_b32_e32 v123, v244, v91, vcc
	v_cmp_le_u32_e32 vcc, v3, v246
	s_and_b64 vcc, s[16:17], vcc
	v_or_b32_e32 v3, 56, v0
	v_cndmask_b32_e32 v108, v244, v76, vcc
	v_cmp_le_u32_e32 vcc, v3, v246
	s_and_b64 vcc, s[16:17], vcc
	v_or_b32_e32 v3, 25, v0
	v_cndmask_b32_e32 v124, v244, v92, vcc
	v_cmp_le_u32_e32 vcc, v3, v246
	s_and_b64 vcc, s[16:17], vcc
	v_or_b32_e32 v3, 57, v0
	v_cndmask_b32_e32 v109, v244, v77, vcc
	v_cmp_le_u32_e32 vcc, v3, v246
	s_and_b64 vcc, s[16:17], vcc
	v_or_b32_e32 v3, 26, v0
	v_cndmask_b32_e32 v125, v244, v93, vcc
	v_cmp_le_u32_e32 vcc, v3, v246
	s_and_b64 vcc, s[16:17], vcc
	v_or_b32_e32 v0, 58, v0
	v_cndmask_b32_e32 v110, v244, v78, vcc
	v_cmp_le_u32_e32 vcc, v0, v246
	s_and_b64 vcc, s[16:17], vcc
	v_or_b32_e32 v0, 27, v1
	v_cndmask_b32_e32 v126, v244, v94, vcc
	v_cmp_le_u32_e32 vcc, v0, v246
	s_and_b64 vcc, s[16:17], vcc
	v_or_b32_e32 v0, 59, v1
	v_cndmask_b32_e32 v111, v244, v79, vcc
	v_cmp_gt_u32_e32 vcc, v0, v246
	s_or_b64 s[12:13], s[12:13], vcc
	v_mov_b32_e32 v127, v95
	s_and_b64 s[12:13], s[12:13], exec
	v_mov_b32_e32 v0, 0xff800000
	s_cbranch_execz .LBB0_957
	v_mov_b64_e32 v[80:81], v[112:113]
	v_mov_b64_e32 v[82:83], v[114:115]
	v_mov_b64_e32 v[84:85], v[116:117]
	v_mov_b64_e32 v[86:87], v[118:119]
	v_mov_b64_e32 v[88:89], v[120:121]
	v_mov_b64_e32 v[90:91], v[122:123]
	v_mov_b64_e32 v[92:93], v[124:125]
	v_mov_b64_e32 v[94:95], v[126:127]
	s_and_saveexec_b64 s[16:17], s[12:13]
	s_cbranch_execnz .LBB0_961
	s_branch .LBB0_962

.LBB0_969:
	v_exp_f32_e32 v96, v96
	v_exp_f32_e32 v80, v80
	v_exp_f32_e32 v97, v97
	v_exp_f32_e32 v81, v81
	v_exp_f32_e32 v98, v98
	v_exp_f32_e32 v82, v82
	v_exp_f32_e32 v99, v99
	v_exp_f32_e32 v83, v83
	v_exp_f32_e32 v100, v100
	v_exp_f32_e32 v84, v84
	v_exp_f32_e32 v101, v101
	v_exp_f32_e32 v85, v85
	v_exp_f32_e32 v102, v102
	v_exp_f32_e32 v86, v86
	v_exp_f32_e32 v103, v103
	v_exp_f32_e32 v87, v87
	v_exp_f32_e32 v104, v104
	v_exp_f32_e32 v88, v88
	v_exp_f32_e32 v105, v105
	v_exp_f32_e32 v89, v89
	v_exp_f32_e32 v106, v106
	v_exp_f32_e32 v90, v90
	v_exp_f32_e32 v107, v107
	v_exp_f32_e32 v91, v91
	v_exp_f32_e32 v108, v108
	v_exp_f32_e32 v92, v92
	v_exp_f32_e32 v109, v109
	v_exp_f32_e32 v93, v93
	v_exp_f32_e32 v110, v110
	v_exp_f32_e32 v94, v94
	v_exp_f32_e32 v111, v111
	v_exp_f32_e32 v95, v95
	s_mov_b64 s[16:17], -1
	v_add_f32_e32 v0, v96, v80
	v_add_f32_e32 v1, v97, v81
	v_add_f32_e32 v3, v98, v82
	v_add_f32_e32 v112, v99, v83
	v_cvt_pk_bf16_f32 v96, v96, v97
	v_add_f32_e32 v0, v0, v100
	v_add_f32_e32 v1, v1, v101
	v_add_f32_e32 v3, v3, v102
	v_add_f32_e32 v112, v112, v103
	v_cvt_pk_bf16_f32 v97, v98, v99
	v_add_f32_e32 v0, v0, v84
	v_add_f32_e32 v1, v1, v85
	v_add_f32_e32 v3, v3, v86
	v_add_f32_e32 v112, v112, v87
	v_cvt_pk_bf16_f32 v98, v100, v101
	v_add_f32_e32 v0, v0, v104
	v_add_f32_e32 v1, v1, v105
	v_add_f32_e32 v3, v3, v106
	v_add_f32_e32 v112, v112, v107
	v_cvt_pk_bf16_f32 v99, v102, v103
	v_add_f32_e32 v0, v0, v88
	v_add_f32_e32 v1, v1, v89
	v_add_f32_e32 v3, v3, v90
	v_add_f32_e32 v112, v112, v91
	v_cvt_pk_bf16_f32 v100, v104, v105
	v_add_f32_e32 v0, v0, v108
	v_add_f32_e32 v1, v1, v109
	v_add_f32_e32 v3, v3, v110
	v_add_f32_e32 v112, v112, v111
	v_cvt_pk_bf16_f32 v101, v106, v107
	v_add_f32_e32 v0, v0, v92
	v_add_f32_e32 v1, v1, v93
	v_add_f32_e32 v3, v3, v94
	v_add_f32_e32 v112, v112, v95
	v_cvt_pk_bf16_f32 v102, v108, v109
	v_add_f32_e32 v0, v0, v1
	v_add_f32_e32 v1, v3, v112
	v_cvt_pk_bf16_f32 v103, v110, v111
	v_add_f32_e32 v0, v0, v1
	v_cvt_pk_bf16_f32 v80, v80, v81
	v_add_f32_e32 v226, v226, v0
	v_cvt_pk_bf16_f32 v81, v82, v83
	v_cvt_pk_bf16_f32 v82, v84, v85
	v_cvt_pk_bf16_f32 v83, v86, v87
	v_cvt_pk_bf16_f32 v84, v88, v89
	v_cvt_pk_bf16_f32 v85, v90, v91
	v_cvt_pk_bf16_f32 v86, v92, v93
	v_cvt_pk_bf16_f32 v87, v94, v95
	v_mfma_f32_32x32x16_bf16 v[32:47], v[4:7], v[96:99], v[32:47]
	s_waitcnt lgkmcnt(12)
	v_mfma_f32_32x32x16_bf16 v[16:31], v[8:11], v[96:99], v[16:31]
	s_waitcnt lgkmcnt(10)
	v_mfma_f32_32x32x16_bf16 v[32:47], v[12:15], v[100:103], v[32:47]
	s_waitcnt lgkmcnt(8)
	v_mfma_f32_32x32x16_bf16 v[16:31], v[164:167], v[100:103], v[16:31]
	s_waitcnt lgkmcnt(6)
	v_mfma_f32_32x32x16_bf16 v[32:47], v[168:171], v[80:83], v[32:47]
	s_waitcnt lgkmcnt(4)
	v_mfma_f32_32x32x16_bf16 v[16:31], v[172:175], v[80:83], v[16:31]
	s_waitcnt lgkmcnt(2)
	v_mfma_f32_32x32x16_bf16 v[32:47], v[176:179], v[84:87], v[32:47]
	s_waitcnt lgkmcnt(0)
	v_mfma_f32_32x32x16_bf16 v[16:31], v[180:183], v[84:87], v[16:31]
	s_cmp_lt_i32 s28, 0
	s_cbranch_scc1 .LBB0_975
	s_lshl_b64 s[12:13], 1, s0
	s_andn2_b64 s[12:13], s[24:25], s[12:13]
	s_ff1_i32_b64 s30, s[12:13]
	s_cmp_lg_u64 s[12:13], 0
	s_cselect_b32 s29, s30, -1
	s_cmp_lt_i32 s29, 0
	s_waitcnt vmcnt(1)
	ds_write_b128 v192, v[156:159] offset:9216
	s_waitcnt vmcnt(0)
	ds_write_b128 v194, v[160:163] offset:30720
	s_waitcnt lgkmcnt(0)
	s_barrier
	s_cbranch_scc1 .LBB0_972
	v_mad_u64_u32 v[0:1], s[16:17], s29, v243, v[224:225]
	global_load_dwordx4 v[156:159], v[0:1], off offset:1536
	global_load_dwordx4 v[160:163], v[0:1], off offset:1792
.LBB0_972:
	ds_read_b128 v[4:7], v239 offset:9216
	ds_read_b128 v[8:11], v239 offset:9248
	ds_read_b128 v[12:15], v239 offset:13824
	ds_read_b128 v[80:83], v239 offset:13856
	ds_read_b128 v[84:87], v239 offset:9280
	ds_read_b128 v[88:91], v239 offset:9312
	ds_read_b128 v[92:95], v239 offset:13888
	ds_read_b128 v[112:115], v239 offset:13920
	v_lshrrev_b64 v[0:1], s28, v[214:215]
	v_and_b32_e32 v0, 1, v0
	s_lshl_b32 s2, s28, 6
	v_cmp_eq_u32_e64 s[16:17], 1, v0
	s_waitcnt lgkmcnt(7)
	v_mfma_f32_32x32x16_bf16 v[96:111], v[4:7], v[132:135], v[64:79]
	s_waitcnt lgkmcnt(5)
	v_mfma_f32_32x32x16_bf16 v[64:79], v[12:15], v[132:135], v[64:79]
	v_mfma_f32_32x32x16_bf16 v[96:111], v[8:11], v[136:139], v[96:111]
	ds_read_b64_tr_b16 v[4:5], v235 offset:30720
	ds_read_b64_tr_b16 v[6:7], v235 offset:32256
	ds_read_b64_tr_b16 v[10:11], v235 offset:32320
	ds_read_b64_tr_b16 v[8:9], v235 offset:30784
	ds_read_b64_tr_b16 v[12:13], v235 offset:33792
	ds_read_b64_tr_b16 v[14:15], v235 offset:35328
	ds_read_b64_tr_b16 v[166:167], v235 offset:35392
	ds_read_b64_tr_b16 v[164:165], v235 offset:33856
	ds_read_b64_tr_b16 v[168:169], v235 offset:36864
	ds_read_b64_tr_b16 v[170:171], v235 offset:38400
	ds_read_b64_tr_b16 v[174:175], v235 offset:38464
	ds_read_b64_tr_b16 v[172:173], v235 offset:36928
	ds_read_b64_tr_b16 v[176:177], v235 offset:39936
	ds_read_b64_tr_b16 v[178:179], v235 offset:41472
	ds_read_b64_tr_b16 v[182:183], v235 offset:41536
	ds_read_b64_tr_b16 v[180:181], v235 offset:40000
	s_waitcnt lgkmcnt(14)
	v_mfma_f32_32x32x16_bf16 v[64:79], v[80:83], v[136:139], v[64:79]
	v_mfma_f32_32x32x16_bf16 v[96:111], v[84:87], v[140:143], v[96:111]
	v_mfma_f32_32x32x16_bf16 v[64:79], v[92:95], v[140:143], v[64:79]
	v_mfma_f32_32x32x16_bf16 v[96:111], v[88:91], v[144:147], v[96:111]
	v_mfma_f32_32x32x16_bf16 v[64:79], v[112:115], v[144:147], v[64:79]
	s_or_b32 s24, s2, 63
	v_cmp_le_u32_e32 vcc, s24, v246
	s_cmp_eq_u64 vcc, exec
	s_cbranch_scc1 .LBB0_976
	v_or_b32_e32 v0, s2, v237
	v_cmp_le_u32_e32 vcc, v0, v246
	s_and_b64 vcc, s[16:17], vcc
	v_or_b32_e32 v1, 32, v0
	s_nop 2
	v_cndmask_b32_e32 v80, v244, v96, vcc
	v_cmp_le_u32_e32 vcc, v1, v246
	s_and_b64 vcc, s[16:17], vcc
	v_or_b32_e32 v1, 33, v0
	v_cndmask_b32_e32 v112, v244, v64, vcc
	v_cmp_lt_u32_e32 vcc, v0, v246
	s_and_b64 vcc, s[16:17], vcc
	s_xor_b64 s[24:25], s[16:17], -1
	v_cndmask_b32_e32 v81, v244, v97, vcc
	v_cmp_le_u32_e32 vcc, v1, v246
	s_and_b64 vcc, s[16:17], vcc
	v_or_b32_e32 v1, 2, v0
	v_cndmask_b32_e32 v113, v244, v65, vcc
	v_cmp_le_u32_e32 vcc, v1, v246
	s_and_b64 vcc, s[16:17], vcc
	v_or_b32_e32 v1, 34, v0
	v_cndmask_b32_e32 v82, v244, v98, vcc
	v_cmp_le_u32_e32 vcc, v1, v246
	v_or_b32_e32 v1, s2, v236
	s_and_b64 vcc, s[16:17], vcc
	v_or_b32_e32 v3, 3, v1
	v_cndmask_b32_e32 v114, v244, v66, vcc
	v_cmp_le_u32_e32 vcc, v3, v246
	s_and_b64 vcc, s[16:17], vcc
	v_or_b32_e32 v3, 35, v1
	v_cndmask_b32_e32 v83, v244, v99, vcc
	v_cmp_le_u32_e32 vcc, v3, v246
	s_and_b64 vcc, s[16:17], vcc
	v_or_b32_e32 v3, 8, v0
	v_cndmask_b32_e32 v115, v244, v67, vcc
	v_cmp_le_u32_e32 vcc, v3, v246
	s_and_b64 vcc, s[16:17], vcc
	v_or_b32_e32 v3, 40, v0
	v_cndmask_b32_e32 v84, v244, v100, vcc
	v_cmp_le_u32_e32 vcc, v3, v246
	s_and_b64 vcc, s[16:17], vcc
	v_or_b32_e32 v3, 9, v0
	v_cndmask_b32_e32 v116, v244, v68, vcc
	v_cmp_le_u32_e32 vcc, v3, v246
	s_and_b64 vcc, s[16:17], vcc
	v_or_b32_e32 v3, 41, v0
	v_cndmask_b32_e32 v85, v244, v101, vcc
	v_cmp_le_u32_e32 vcc, v3, v246
	s_and_b64 vcc, s[16:17], vcc
	v_or_b32_e32 v3, 10, v0
	v_cndmask_b32_e32 v117, v244, v69, vcc
	v_cmp_le_u32_e32 vcc, v3, v246
	s_and_b64 vcc, s[16:17], vcc
	v_or_b32_e32 v3, 42, v0
	v_cndmask_b32_e32 v86, v244, v102, vcc
	v_cmp_le_u32_e32 vcc, v3, v246
	s_and_b64 vcc, s[16:17], vcc
	v_or_b32_e32 v3, 11, v1
	v_cndmask_b32_e32 v118, v244, v70, vcc
	v_cmp_le_u32_e32 vcc, v3, v246
	s_and_b64 vcc, s[16:17], vcc
	v_or_b32_e32 v3, 43, v1
	v_cndmask_b32_e32 v87, v244, v103, vcc
	v_cmp_le_u32_e32 vcc, v3, v246
	s_and_b64 vcc, s[16:17], vcc
	v_or_b32_e32 v3, 16, v0
	v_cndmask_b32_e32 v119, v244, v71, vcc
	v_cmp_le_u32_e32 vcc, v3, v246
	s_and_b64 vcc, s[16:17], vcc
	v_or_b32_e32 v3, 48, v0
	v_cndmask_b32_e32 v88, v244, v104, vcc
	v_cmp_le_u32_e32 vcc, v3, v246
	s_and_b64 vcc, s[16:17], vcc
	v_or_b32_e32 v3, 17, v0
	v_cndmask_b32_e32 v120, v244, v72, vcc
	v_cmp_le_u32_e32 vcc, v3, v246
	s_and_b64 vcc, s[16:17], vcc
	v_or_b32_e32 v3, 49, v0
	v_cndmask_b32_e32 v89, v244, v105, vcc
	v_cmp_le_u32_e32 vcc, v3, v246
	s_and_b64 vcc, s[16:17], vcc
	v_or_b32_e32 v3, 18, v0
	v_cndmask_b32_e32 v121, v244, v73, vcc
	v_cmp_le_u32_e32 vcc, v3, v246
	s_and_b64 vcc, s[16:17], vcc
	v_or_b32_e32 v3, 50, v0
	v_cndmask_b32_e32 v90, v244, v106, vcc
	v_cmp_le_u32_e32 vcc, v3, v246
	s_and_b64 vcc, s[16:17], vcc
	v_or_b32_e32 v3, 19, v1
	v_cndmask_b32_e32 v122, v244, v74, vcc
	v_cmp_le_u32_e32 vcc, v3, v246
	s_and_b64 vcc, s[16:17], vcc
	v_or_b32_e32 v3, 51, v1
	v_cndmask_b32_e32 v91, v244, v107, vcc
	v_cmp_le_u32_e32 vcc, v3, v246
	s_and_b64 vcc, s[16:17], vcc
	v_or_b32_e32 v3, 24, v0
	v_cndmask_b32_e32 v123, v244, v75, vcc
	v_cmp_le_u32_e32 vcc, v3, v246
	s_and_b64 vcc, s[16:17], vcc
	v_or_b32_e32 v3, 56, v0
	v_cndmask_b32_e32 v92, v244, v108, vcc
	v_cmp_le_u32_e32 vcc, v3, v246
	s_and_b64 vcc, s[16:17], vcc
	v_or_b32_e32 v3, 25, v0
	v_cndmask_b32_e32 v124, v244, v76, vcc
	v_cmp_le_u32_e32 vcc, v3, v246
	s_and_b64 vcc, s[16:17], vcc
	v_or_b32_e32 v3, 57, v0
	v_cndmask_b32_e32 v93, v244, v109, vcc
	v_cmp_le_u32_e32 vcc, v3, v246
	s_and_b64 vcc, s[16:17], vcc
	v_or_b32_e32 v3, 26, v0
	v_cndmask_b32_e32 v125, v244, v77, vcc
	v_cmp_le_u32_e32 vcc, v3, v246
	s_and_b64 vcc, s[16:17], vcc
	v_or_b32_e32 v0, 58, v0
	v_cndmask_b32_e32 v94, v244, v110, vcc
	v_cmp_le_u32_e32 vcc, v0, v246
	s_and_b64 vcc, s[16:17], vcc
	v_or_b32_e32 v0, 27, v1
	v_cndmask_b32_e32 v126, v244, v78, vcc
	v_cmp_le_u32_e32 vcc, v0, v246
	s_and_b64 vcc, s[16:17], vcc
	v_or_b32_e32 v0, 59, v1
	v_cndmask_b32_e32 v95, v244, v111, vcc
	v_cmp_gt_u32_e32 vcc, v0, v246
	s_or_b64 s[24:25], s[24:25], vcc
	v_mov_b32_e32 v127, v79
	s_and_b64 s[24:25], s[24:25], exec
	v_mov_b32_e32 v0, 0xff800000
	s_cbranch_execz .LBB0_977
	v_mov_b64_e32 v[64:65], v[112:113]
	v_mov_b64_e32 v[66:67], v[114:115]
	v_mov_b64_e32 v[68:69], v[116:117]
	v_mov_b64_e32 v[70:71], v[118:119]
	v_mov_b64_e32 v[72:73], v[120:121]
	v_mov_b64_e32 v[74:75], v[122:123]
	v_mov_b64_e32 v[76:77], v[124:125]
	v_mov_b64_e32 v[78:79], v[126:127]
	s_and_saveexec_b64 s[16:17], s[24:25]
	s_cbranch_execnz .LBB0_981
	s_branch .LBB0_982

.LBB0_988:
	v_exp_f32_e32 v80, v80
	v_exp_f32_e32 v64, v64
	v_exp_f32_e32 v81, v81
	v_exp_f32_e32 v65, v65
	v_exp_f32_e32 v82, v82
	v_exp_f32_e32 v66, v66
	v_exp_f32_e32 v83, v83
	v_exp_f32_e32 v67, v67
	v_exp_f32_e32 v84, v84
	v_exp_f32_e32 v68, v68
	v_exp_f32_e32 v85, v85
	v_exp_f32_e32 v69, v69
	v_exp_f32_e32 v86, v86
	v_exp_f32_e32 v70, v70
	v_exp_f32_e32 v87, v87
	v_exp_f32_e32 v71, v71
	v_exp_f32_e32 v88, v88
	v_exp_f32_e32 v72, v72
	v_exp_f32_e32 v89, v89
	v_exp_f32_e32 v73, v73
	v_exp_f32_e32 v90, v90
	v_exp_f32_e32 v74, v74
	v_exp_f32_e32 v91, v91
	v_exp_f32_e32 v75, v75
	v_exp_f32_e32 v92, v92
	v_exp_f32_e32 v76, v76
	v_exp_f32_e32 v93, v93
	v_exp_f32_e32 v77, v77
	v_exp_f32_e32 v94, v94
	v_exp_f32_e32 v78, v78
	v_exp_f32_e32 v95, v95
	v_exp_f32_e32 v79, v79
	v_add_f32_e32 v0, v80, v64
	v_add_f32_e32 v1, v81, v65
	v_add_f32_e32 v3, v82, v66
	v_add_f32_e32 v96, v83, v67
	v_cvt_pk_bf16_f32 v80, v80, v81
	v_add_f32_e32 v0, v0, v84
	v_add_f32_e32 v1, v1, v85
	v_add_f32_e32 v3, v3, v86
	v_add_f32_e32 v96, v96, v87
	v_cvt_pk_bf16_f32 v81, v82, v83
	v_add_f32_e32 v0, v0, v68
	v_add_f32_e32 v1, v1, v69
	v_add_f32_e32 v3, v3, v70
	v_add_f32_e32 v96, v96, v71
	v_cvt_pk_bf16_f32 v82, v84, v85
	v_add_f32_e32 v0, v0, v88
	v_add_f32_e32 v1, v1, v89
	v_add_f32_e32 v3, v3, v90
	v_add_f32_e32 v96, v96, v91
	v_cvt_pk_bf16_f32 v83, v86, v87
	v_add_f32_e32 v0, v0, v72
	v_add_f32_e32 v1, v1, v73
	v_add_f32_e32 v3, v3, v74
	v_add_f32_e32 v96, v96, v75
	v_cvt_pk_bf16_f32 v84, v88, v89
	v_add_f32_e32 v0, v0, v92
	v_add_f32_e32 v1, v1, v93
	v_add_f32_e32 v3, v3, v94
	v_add_f32_e32 v96, v96, v95
	v_cvt_pk_bf16_f32 v85, v90, v91
	v_add_f32_e32 v0, v0, v76
	v_add_f32_e32 v1, v1, v77
	v_add_f32_e32 v3, v3, v78
	v_add_f32_e32 v96, v96, v79
	v_cvt_pk_bf16_f32 v86, v92, v93
	v_add_f32_e32 v0, v0, v1
	v_add_f32_e32 v1, v3, v96
	v_cvt_pk_bf16_f32 v87, v94, v95
	v_add_f32_e32 v0, v0, v1
	v_cvt_pk_bf16_f32 v64, v64, v65
	v_cvt_pk_bf16_f32 v65, v66, v67
	v_cvt_pk_bf16_f32 v66, v68, v69
	v_cvt_pk_bf16_f32 v67, v70, v71
	v_cvt_pk_bf16_f32 v68, v72, v73
	v_cvt_pk_bf16_f32 v69, v74, v75
	v_cvt_pk_bf16_f32 v70, v76, v77
	v_cvt_pk_bf16_f32 v71, v78, v79
	v_mfma_f32_32x32x16_bf16 v[32:47], v[4:7], v[80:83], v[32:47]
	s_waitcnt lgkmcnt(12)
	v_mfma_f32_32x32x16_bf16 v[16:31], v[8:11], v[80:83], v[16:31]
	s_waitcnt lgkmcnt(10)
	v_mfma_f32_32x32x16_bf16 v[32:47], v[12:15], v[84:87], v[32:47]
	s_waitcnt lgkmcnt(8)
	v_mfma_f32_32x32x16_bf16 v[16:31], v[164:167], v[84:87], v[16:31]
	s_waitcnt lgkmcnt(6)
	v_mfma_f32_32x32x16_bf16 v[32:47], v[168:171], v[64:67], v[32:47]
	s_waitcnt lgkmcnt(4)
	v_mfma_f32_32x32x16_bf16 v[16:31], v[172:175], v[64:67], v[16:31]
	s_waitcnt lgkmcnt(2)
	v_mfma_f32_32x32x16_bf16 v[32:47], v[176:179], v[68:71], v[32:47]
	s_waitcnt lgkmcnt(0)
	v_mfma_f32_32x32x16_bf16 v[16:31], v[180:183], v[68:71], v[16:31]
	s_andn2_b64 vcc, exec, s[22:23]
	s_mov_b64 s[16:17], -1
	s_cbranch_vccnz .LBB0_950
	s_lshl_b64 s[16:17], 1, s30
	s_andn2_b64 s[24:25], s[12:13], s[16:17]
	s_mov_b64 s[16:17], 0
	s_waitcnt vmcnt(1)
	ds_write_b128 v192, v[148:151]
	s_waitcnt vmcnt(0)
	ds_write_b128 v194, v[152:155] offset:18432
	s_waitcnt lgkmcnt(0)
	s_barrier
	s_branch .LBB0_950

.LBB0_999:
	ds_read_b128 v[4:7], v239
	ds_read_b128 v[8:11], v239 offset:32
	ds_read_b128 v[12:15], v239 offset:4608
	ds_read_b128 v[64:67], v239 offset:4640
	ds_read_b128 v[68:71], v239 offset:64
	ds_read_b128 v[72:75], v239 offset:96
	ds_read_b128 v[76:79], v239 offset:4672
	ds_read_b128 v[112:115], v239 offset:4704
	s_lshl_b32 s2, s2, 6
	s_waitcnt lgkmcnt(7)
	v_mfma_f32_32x32x16_bf16 v[80:95], v[4:7], v[132:135], v[48:63]
	s_waitcnt lgkmcnt(5)
	v_mfma_f32_32x32x16_bf16 v[96:111], v[12:15], v[132:135], v[48:63]
	v_mfma_f32_32x32x16_bf16 v[80:95], v[8:11], v[136:139], v[80:95]
	ds_read_b64_tr_b16 v[4:5], v235 offset:18432
	ds_read_b64_tr_b16 v[6:7], v235 offset:19968
	ds_read_b64_tr_b16 v[10:11], v235 offset:20032
	ds_read_b64_tr_b16 v[8:9], v235 offset:18496
	ds_read_b64_tr_b16 v[12:13], v235 offset:21504
	ds_read_b64_tr_b16 v[14:15], v235 offset:23040
	ds_read_b64_tr_b16 v[166:167], v235 offset:23104
	ds_read_b64_tr_b16 v[164:165], v235 offset:21568
	ds_read_b64_tr_b16 v[168:169], v235 offset:24576
	ds_read_b64_tr_b16 v[170:171], v235 offset:26112
	ds_read_b64_tr_b16 v[174:175], v235 offset:26176
	ds_read_b64_tr_b16 v[172:173], v235 offset:24640
	ds_read_b64_tr_b16 v[176:177], v235 offset:27648
	ds_read_b64_tr_b16 v[178:179], v235 offset:29184
	ds_read_b64_tr_b16 v[182:183], v235 offset:29248
	ds_read_b64_tr_b16 v[180:181], v235 offset:27712
	s_waitcnt lgkmcnt(14)
	v_mfma_f32_32x32x16_bf16 v[96:111], v[64:67], v[136:139], v[96:111]
	v_mfma_f32_32x32x16_bf16 v[80:95], v[68:71], v[140:143], v[80:95]
	v_mfma_f32_32x32x16_bf16 v[96:111], v[76:79], v[140:143], v[96:111]
	v_mfma_f32_32x32x16_bf16 v[80:95], v[72:75], v[144:147], v[80:95]
	v_mfma_f32_32x32x16_bf16 v[96:111], v[112:115], v[144:147], v[96:111]
	s_or_b32 s16, s2, 63
	v_cmp_ge_i32_e32 vcc, s2, v226
	v_cmp_le_u32_e64 s[16:17], s16, v246
	s_and_b64 s[16:17], vcc, s[16:17]
	s_nop 0
	s_cmp_eq_u64 s[16:17], exec
	s_cbranch_scc1 .LBB0_1003
	v_or_b32_e32 v0, s2, v237
	v_or_b32_e32 v1, 32, v0
	v_cmp_lt_i32_e64 s[18:19], v1, v226
	v_cmp_gt_u32_e64 s[20:21], v1, v246
	s_or_b64 s[18:19], s[18:19], s[20:21]
	v_or_b32_e32 v1, 1, v0
	v_cndmask_b32_e64 v96, v96, v244, s[18:19]
	v_cmp_ge_i32_e64 s[18:19], v1, v226
	v_or_b32_e32 v1, 33, v0
	v_cmp_lt_i32_e64 s[22:23], v1, v226
	v_cmp_gt_u32_e64 s[24:25], v1, v246
	s_or_b64 s[22:23], s[22:23], s[24:25]
	v_or_b32_e32 v1, 2, v0
	v_cndmask_b32_e64 v97, v97, v244, s[22:23]
	v_cmp_ge_i32_e64 s[22:23], v1, v226
	v_cmp_le_u32_e64 s[24:25], v1, v246
	v_or_b32_e32 v1, 34, v0
	v_cmp_lt_i32_e64 s[26:27], v1, v226
	v_cmp_gt_u32_e64 s[28:29], v1, v246
	v_or_b32_e32 v1, s2, v236
	s_or_b64 s[26:27], s[26:27], s[28:29]
	v_or_b32_e32 v3, 3, v1
	v_cndmask_b32_e64 v98, v98, v244, s[26:27]
	v_cmp_ge_i32_e64 s[26:27], v3, v226
	v_cmp_le_u32_e64 s[28:29], v3, v246
	v_or_b32_e32 v3, 35, v1
	v_cmp_lt_i32_e64 s[30:31], v3, v226
	v_cmp_gt_u32_e64 s[34:35], v3, v246
	s_or_b64 s[30:31], s[30:31], s[34:35]
	v_or_b32_e32 v3, 8, v0
	v_cndmask_b32_e64 v99, v99, v244, s[30:31]
	v_cmp_ge_i32_e64 s[30:31], v3, v226
	v_cmp_le_u32_e64 s[34:35], v3, v246
	v_or_b32_e32 v3, 40, v0
	v_cmp_lt_i32_e64 s[36:37], v3, v226
	v_cmp_gt_u32_e64 s[38:39], v3, v246
	s_or_b64 s[36:37], s[36:37], s[38:39]
	v_or_b32_e32 v3, 9, v0
	v_cndmask_b32_e64 v100, v100, v244, s[36:37]
	v_cmp_ge_i32_e64 s[36:37], v3, v226
	v_cmp_le_u32_e64 s[38:39], v3, v246
	v_or_b32_e32 v3, 41, v0
	v_cmp_lt_i32_e64 s[40:41], v3, v226
	v_cmp_gt_u32_e64 s[42:43], v3, v246
	s_or_b64 s[40:41], s[40:41], s[42:43]
	v_or_b32_e32 v3, 10, v0
	v_cndmask_b32_e64 v101, v101, v244, s[40:41]
	v_cmp_ge_i32_e64 s[40:41], v3, v226
	v_cmp_le_u32_e64 s[42:43], v3, v246
	v_or_b32_e32 v3, 42, v0
	v_cmp_lt_i32_e64 s[44:45], v3, v226
	v_cmp_gt_u32_e64 s[46:47], v3, v246
	s_or_b64 s[44:45], s[44:45], s[46:47]
	v_or_b32_e32 v3, 11, v1
	v_cndmask_b32_e64 v102, v102, v244, s[44:45]
	v_cmp_ge_i32_e64 s[44:45], v3, v226
	v_cmp_le_u32_e64 s[46:47], v3, v246
	v_or_b32_e32 v3, 43, v1
	v_cmp_lt_i32_e64 s[48:49], v3, v226
	v_cmp_gt_u32_e64 s[50:51], v3, v246
	s_or_b64 s[48:49], s[48:49], s[50:51]
	v_or_b32_e32 v3, 16, v0
	v_cndmask_b32_e64 v103, v103, v244, s[48:49]
	v_cmp_ge_i32_e64 s[48:49], v3, v226
	v_cmp_le_u32_e64 s[50:51], v3, v246
	v_or_b32_e32 v3, 48, v0
	v_cmp_lt_i32_e64 s[52:53], v3, v226
	v_cmp_gt_u32_e64 s[54:55], v3, v246
	s_or_b64 s[52:53], s[52:53], s[54:55]
	v_or_b32_e32 v3, 17, v0
	v_cndmask_b32_e64 v104, v104, v244, s[52:53]
	v_cmp_ge_i32_e64 s[52:53], v3, v226
	v_cmp_le_u32_e64 s[54:55], v3, v246
	v_or_b32_e32 v3, 49, v0
	v_cmp_lt_i32_e64 s[56:57], v3, v226
	v_cmp_gt_u32_e64 s[58:59], v3, v246
	s_or_b64 s[56:57], s[56:57], s[58:59]
	v_or_b32_e32 v3, 18, v0
	v_cndmask_b32_e64 v105, v105, v244, s[56:57]
	v_cmp_ge_i32_e64 s[56:57], v3, v226
	v_cmp_le_u32_e64 s[58:59], v3, v246
	v_or_b32_e32 v3, 50, v0
	v_cmp_lt_i32_e64 s[60:61], v3, v226
	v_cmp_gt_u32_e64 s[62:63], v3, v246
	s_or_b64 s[60:61], s[60:61], s[62:63]
	v_or_b32_e32 v3, 19, v1
	v_cndmask_b32_e64 v106, v106, v244, s[60:61]
	v_cmp_ge_i32_e64 s[60:61], v3, v226
	v_cmp_le_u32_e64 s[62:63], v3, v246
	v_or_b32_e32 v3, 51, v1
	v_cmp_lt_i32_e64 s[64:65], v3, v226
	v_cmp_gt_u32_e64 s[66:67], v3, v246
	s_or_b64 s[64:65], s[64:65], s[66:67]
	v_or_b32_e32 v3, 24, v0
	v_cndmask_b32_e64 v107, v107, v244, s[64:65]
	v_cmp_ge_i32_e64 s[64:65], v3, v226
	v_cmp_le_u32_e64 s[66:67], v3, v246
	v_or_b32_e32 v3, 56, v0
	v_cmp_lt_i32_e64 s[68:69], v3, v226
	v_cmp_gt_u32_e64 s[70:71], v3, v246
	s_or_b64 s[68:69], s[68:69], s[70:71]
	v_or_b32_e32 v3, 25, v0
	v_cndmask_b32_e64 v108, v108, v244, s[68:69]
	v_cmp_ge_i32_e64 s[68:69], v3, v226
	v_cmp_le_u32_e64 s[70:71], v3, v246
	v_or_b32_e32 v3, 57, v0
	v_cmp_ge_i32_e32 vcc, v0, v226
	v_cmp_le_u32_e64 s[16:17], v0, v246
	v_cmp_lt_u32_e64 s[20:21], v0, v246
	v_cmp_lt_i32_e64 s[72:73], v3, v226
	v_cmp_gt_u32_e64 s[74:75], v3, v246
	v_or_b32_e32 v3, 26, v0
	v_or_b32_e32 v0, 58, v0
	v_cmp_lt_i32_e64 s[76:77], v0, v226
	v_cmp_gt_u32_e64 s[78:79], v0, v246
	s_or_b64 s[76:77], s[76:77], s[78:79]
	v_or_b32_e32 v0, 27, v1
	v_cndmask_b32_e64 v110, v110, v244, s[76:77]
	v_cmp_ge_i32_e64 s[76:77], v0, v226
	v_cmp_le_u32_e64 s[78:79], v0, v246
	v_or_b32_e32 v0, 59, v1
	s_or_b64 s[72:73], s[72:73], s[74:75]
	v_cmp_lt_i32_e64 s[82:83], v0, v226
	v_cmp_gt_u32_e64 s[84:85], v0, v246
	v_cndmask_b32_e64 v109, v109, v244, s[72:73]
	v_cmp_ge_i32_e64 s[72:73], v3, v226
	v_cmp_le_u32_e64 s[74:75], v3, v246
	s_or_b64 s[84:85], s[82:83], s[84:85]
	s_and_saveexec_b64 s[82:83], s[84:85]
	v_mov_b32_e32 v111, s5
	s_or_b64 exec, exec, s[82:83]
	s_and_b64 vcc, vcc, s[16:17]
	v_cndmask_b32_e32 v80, v244, v80, vcc
	s_and_b64 vcc, s[20:21], s[18:19]
	v_cndmask_b32_e32 v81, v244, v81, vcc
	s_and_b64 vcc, s[22:23], s[24:25]
	v_cndmask_b32_e32 v82, v244, v82, vcc
	s_and_b64 vcc, s[26:27], s[28:29]
	v_cndmask_b32_e32 v83, v244, v83, vcc
	s_and_b64 vcc, s[30:31], s[34:35]
	v_cndmask_b32_e32 v84, v244, v84, vcc
	s_and_b64 vcc, s[36:37], s[38:39]
	v_cndmask_b32_e32 v85, v244, v85, vcc
	s_and_b64 vcc, s[40:41], s[42:43]
	v_cndmask_b32_e32 v86, v244, v86, vcc
	s_and_b64 vcc, s[44:45], s[46:47]
	v_cndmask_b32_e32 v87, v244, v87, vcc
	s_and_b64 vcc, s[48:49], s[50:51]
	v_cndmask_b32_e32 v88, v244, v88, vcc
	s_and_b64 vcc, s[52:53], s[54:55]
	v_cndmask_b32_e32 v89, v244, v89, vcc
	s_and_b64 vcc, s[56:57], s[58:59]
	v_cndmask_b32_e32 v90, v244, v90, vcc
	s_and_b64 vcc, s[60:61], s[62:63]
	v_cndmask_b32_e32 v91, v244, v91, vcc
	s_and_b64 vcc, s[64:65], s[66:67]
	v_cndmask_b32_e32 v92, v244, v92, vcc
	s_and_b64 vcc, s[68:69], s[70:71]
	v_cndmask_b32_e32 v93, v244, v93, vcc
	s_and_b64 vcc, s[72:73], s[74:75]
	v_cndmask_b32_e32 v94, v244, v94, vcc
	s_and_b64 vcc, s[76:77], s[78:79]
	v_cndmask_b32_e32 v95, v244, v95, vcc

.LBB0_1010:
	v_exp_f32_e32 v112, v80
	v_exp_f32_e32 v80, v96
	v_exp_f32_e32 v113, v81
	v_exp_f32_e32 v81, v97
	v_exp_f32_e32 v114, v82
	v_exp_f32_e32 v82, v98
	v_exp_f32_e32 v115, v83
	v_exp_f32_e32 v83, v99
	v_exp_f32_e32 v116, v84
	v_exp_f32_e32 v84, v100
	v_exp_f32_e32 v117, v85
	v_exp_f32_e32 v85, v101
	v_exp_f32_e32 v118, v86
	v_exp_f32_e32 v86, v102
	v_exp_f32_e32 v119, v87
	v_exp_f32_e32 v87, v103
	v_exp_f32_e32 v120, v88
	v_exp_f32_e32 v88, v104
	v_exp_f32_e32 v121, v89
	v_exp_f32_e32 v89, v105
	v_exp_f32_e32 v122, v90
	v_exp_f32_e32 v90, v106
	v_exp_f32_e32 v123, v91
	v_exp_f32_e32 v91, v107
	v_exp_f32_e32 v124, v92
	v_exp_f32_e32 v92, v108
	v_exp_f32_e32 v125, v93
	v_exp_f32_e32 v93, v109
	v_exp_f32_e32 v126, v94
	v_exp_f32_e32 v94, v110
	v_exp_f32_e32 v127, v95
	v_exp_f32_e32 v95, v111
	s_mov_b64 s[16:17], -1
	v_add_f32_e32 v0, v112, v80
	v_add_f32_e32 v1, v113, v81
	v_add_f32_e32 v3, v114, v82
	v_add_f32_e32 v96, v115, v83
	v_cvt_pk_bf16_f32 v97, v114, v115
	v_add_f32_e32 v0, v0, v116
	v_add_f32_e32 v1, v1, v117
	v_add_f32_e32 v3, v3, v118
	v_add_f32_e32 v96, v96, v119
	v_cvt_pk_bf16_f32 v98, v116, v117
	v_add_f32_e32 v0, v0, v84
	v_add_f32_e32 v1, v1, v85
	v_add_f32_e32 v3, v3, v86
	v_add_f32_e32 v96, v96, v87
	v_cvt_pk_bf16_f32 v99, v118, v119
	v_add_f32_e32 v0, v0, v120
	v_add_f32_e32 v1, v1, v121
	v_add_f32_e32 v3, v3, v122
	v_add_f32_e32 v96, v96, v123
	v_cvt_pk_bf16_f32 v100, v120, v121
	v_add_f32_e32 v0, v0, v88
	v_add_f32_e32 v1, v1, v89
	v_add_f32_e32 v3, v3, v90
	v_add_f32_e32 v96, v96, v91
	v_cvt_pk_bf16_f32 v101, v122, v123
	v_add_f32_e32 v0, v0, v124
	v_add_f32_e32 v1, v1, v125
	v_add_f32_e32 v3, v3, v126
	v_add_f32_e32 v96, v96, v127
	v_cvt_pk_bf16_f32 v102, v124, v125
	v_add_f32_e32 v0, v0, v92
	v_add_f32_e32 v1, v1, v93
	v_add_f32_e32 v3, v3, v94
	v_add_f32_e32 v96, v96, v95
	v_cvt_pk_bf16_f32 v103, v126, v127
	v_add_f32_e32 v0, v0, v1
	v_add_f32_e32 v1, v3, v96
	v_cvt_pk_bf16_f32 v96, v112, v113
	v_add_f32_e32 v0, v0, v1
	v_cvt_pk_bf16_f32 v80, v80, v81
	v_add_f32_e32 v222, v222, v0
	v_cvt_pk_bf16_f32 v81, v82, v83
	v_cvt_pk_bf16_f32 v82, v84, v85
	v_cvt_pk_bf16_f32 v83, v86, v87
	v_cvt_pk_bf16_f32 v84, v88, v89
	v_cvt_pk_bf16_f32 v85, v90, v91
	v_cvt_pk_bf16_f32 v86, v92, v93
	v_cvt_pk_bf16_f32 v87, v94, v95
	v_mfma_f32_32x32x16_bf16 v[32:47], v[4:7], v[96:99], v[32:47]
	s_waitcnt lgkmcnt(12)
	v_mfma_f32_32x32x16_bf16 v[16:31], v[8:11], v[96:99], v[16:31]
	s_waitcnt lgkmcnt(10)
	v_mfma_f32_32x32x16_bf16 v[32:47], v[12:15], v[100:103], v[32:47]
	s_waitcnt lgkmcnt(8)
	v_mfma_f32_32x32x16_bf16 v[16:31], v[164:167], v[100:103], v[16:31]
	s_waitcnt lgkmcnt(6)
	v_mfma_f32_32x32x16_bf16 v[32:47], v[168:171], v[80:83], v[32:47]
	s_waitcnt lgkmcnt(4)
	v_mfma_f32_32x32x16_bf16 v[16:31], v[172:175], v[80:83], v[16:31]
	s_waitcnt lgkmcnt(2)
	v_mfma_f32_32x32x16_bf16 v[32:47], v[176:179], v[84:87], v[32:47]
	s_waitcnt lgkmcnt(0)
	v_mfma_f32_32x32x16_bf16 v[16:31], v[180:183], v[84:87], v[16:31]
	s_cmp_lt_i32 s33, 0
	s_cbranch_scc1 .LBB0_1025
	s_lshl_b64 s[16:17], 1, s0
	s_andn2_b64 s[86:87], s[12:13], s[16:17]
	s_ff1_i32_b64 s96, s[86:87]
	s_cmp_lg_u64 s[86:87], 0
	s_cselect_b32 s2, s96, -1
	s_cmp_lt_i32 s2, 0
	s_waitcnt vmcnt(1)
	ds_write_b128 v192, v[156:159] offset:9216
	s_waitcnt vmcnt(0)
	ds_write_b128 v194, v[160:163] offset:30720
	s_waitcnt lgkmcnt(0)
	s_barrier
	s_cbranch_scc1 .LBB0_1013
	v_mad_u64_u32 v[0:1], s[12:13], s2, v243, v[228:229]
	global_load_dwordx4 v[156:159], v[0:1], off offset:2048
	global_load_dwordx4 v[160:163], v[0:1], off offset:2304
.LBB0_1013:
	ds_read_b128 v[4:7], v239 offset:9216
	ds_read_b128 v[8:11], v239 offset:9248
	ds_read_b128 v[12:15], v239 offset:13824
	ds_read_b128 v[96:99], v239 offset:13856
	ds_read_b128 v[100:103], v239 offset:9280
	ds_read_b128 v[104:107], v239 offset:9312
	ds_read_b128 v[108:111], v239 offset:13888
	ds_read_b128 v[116:119], v239 offset:13920
	s_lshl_b32 s12, s33, 6
	s_waitcnt lgkmcnt(7)
	v_mfma_f32_32x32x16_bf16 v[80:95], v[4:7], v[132:135], v[64:79]
	s_waitcnt lgkmcnt(5)
	v_mfma_f32_32x32x16_bf16 v[64:79], v[12:15], v[132:135], v[64:79]
	v_mfma_f32_32x32x16_bf16 v[80:95], v[8:11], v[136:139], v[80:95]
	s_waitcnt lgkmcnt(4)
	v_mfma_f32_32x32x16_bf16 v[64:79], v[96:99], v[136:139], v[64:79]
	ds_read_b64_tr_b16 v[4:5], v235 offset:30720
	ds_read_b64_tr_b16 v[6:7], v235 offset:32256
	ds_read_b64_tr_b16 v[10:11], v235 offset:32320
	ds_read_b64_tr_b16 v[8:9], v235 offset:30784
	ds_read_b64_tr_b16 v[12:13], v235 offset:33792
	ds_read_b64_tr_b16 v[14:15], v235 offset:35328
	ds_read_b64_tr_b16 v[98:99], v235 offset:35392
	ds_read_b64_tr_b16 v[96:97], v235 offset:33856
	s_waitcnt lgkmcnt(11)
	v_mfma_f32_32x32x16_bf16 v[80:95], v[100:103], v[140:143], v[80:95]
	s_waitcnt lgkmcnt(9)
	v_mfma_f32_32x32x16_bf16 v[64:79], v[108:111], v[140:143], v[64:79]
	v_mfma_f32_32x32x16_bf16 v[80:95], v[104:107], v[144:147], v[80:95]
	ds_read_b64_tr_b16 v[100:101], v235 offset:36864
	ds_read_b64_tr_b16 v[102:103], v235 offset:38400
	ds_read_b64_tr_b16 v[106:107], v235 offset:38464
	ds_read_b64_tr_b16 v[104:105], v235 offset:36928
	ds_read_b64_tr_b16 v[108:109], v235 offset:39936
	ds_read_b64_tr_b16 v[110:111], v235 offset:41472
	ds_read_b64_tr_b16 v[114:115], v235 offset:41536
	ds_read_b64_tr_b16 v[112:113], v235 offset:40000
	s_waitcnt lgkmcnt(14)
	v_mfma_f32_32x32x16_bf16 v[64:79], v[116:119], v[144:147], v[64:79]
	s_or_b32 s13, s12, 63
	v_cmp_ge_i32_e32 vcc, s12, v226
	v_cmp_le_u32_e64 s[16:17], s13, v246
	s_and_b64 s[16:17], vcc, s[16:17]
	s_nop 0
	s_cmp_eq_u64 s[16:17], exec
	s_cbranch_scc1 .LBB0_1017
	v_or_b32_e32 v0, s12, v237
	v_or_b32_e32 v1, 32, v0
	v_cmp_lt_i32_e64 s[18:19], v1, v226
	v_cmp_gt_u32_e64 s[20:21], v1, v246
	s_or_b64 s[18:19], s[18:19], s[20:21]
	v_or_b32_e32 v1, 1, v0
	v_cndmask_b32_e64 v64, v64, v244, s[18:19]
	v_cmp_ge_i32_e64 s[18:19], v1, v226
	v_or_b32_e32 v1, 33, v0
	v_cmp_lt_i32_e64 s[22:23], v1, v226
	v_cmp_gt_u32_e64 s[24:25], v1, v246
	s_or_b64 s[22:23], s[22:23], s[24:25]
	v_or_b32_e32 v1, 2, v0
	v_cndmask_b32_e64 v65, v65, v244, s[22:23]
	v_cmp_ge_i32_e64 s[22:23], v1, v226
	v_cmp_le_u32_e64 s[24:25], v1, v246
	v_or_b32_e32 v1, 34, v0
	v_cmp_lt_i32_e64 s[26:27], v1, v226
	v_cmp_gt_u32_e64 s[28:29], v1, v246
	v_or_b32_e32 v1, s12, v236
	s_or_b64 s[26:27], s[26:27], s[28:29]
	v_or_b32_e32 v3, 3, v1
	v_cndmask_b32_e64 v66, v66, v244, s[26:27]
	v_cmp_ge_i32_e64 s[26:27], v3, v226
	v_cmp_le_u32_e64 s[28:29], v3, v246
	v_or_b32_e32 v3, 35, v1
	v_cmp_lt_i32_e64 s[30:31], v3, v226
	v_cmp_gt_u32_e64 s[34:35], v3, v246
	s_or_b64 s[30:31], s[30:31], s[34:35]
	v_or_b32_e32 v3, 8, v0
	v_cndmask_b32_e64 v67, v67, v244, s[30:31]
	v_cmp_ge_i32_e64 s[30:31], v3, v226
	v_cmp_le_u32_e64 s[34:35], v3, v246
	v_or_b32_e32 v3, 40, v0
	v_cmp_lt_i32_e64 s[36:37], v3, v226
	v_cmp_gt_u32_e64 s[38:39], v3, v246
	s_or_b64 s[36:37], s[36:37], s[38:39]
	v_or_b32_e32 v3, 9, v0
	v_cndmask_b32_e64 v68, v68, v244, s[36:37]
	v_cmp_ge_i32_e64 s[36:37], v3, v226
	v_cmp_le_u32_e64 s[38:39], v3, v246
	v_or_b32_e32 v3, 41, v0
	v_cmp_lt_i32_e64 s[40:41], v3, v226
	v_cmp_gt_u32_e64 s[42:43], v3, v246
	s_or_b64 s[40:41], s[40:41], s[42:43]
	v_or_b32_e32 v3, 10, v0
	v_cndmask_b32_e64 v69, v69, v244, s[40:41]
	v_cmp_ge_i32_e64 s[40:41], v3, v226
	v_cmp_le_u32_e64 s[42:43], v3, v246
	v_or_b32_e32 v3, 42, v0
	v_cmp_lt_i32_e64 s[44:45], v3, v226
	v_cmp_gt_u32_e64 s[46:47], v3, v246
	s_or_b64 s[44:45], s[44:45], s[46:47]
	v_or_b32_e32 v3, 11, v1
	v_cndmask_b32_e64 v70, v70, v244, s[44:45]
	v_cmp_ge_i32_e64 s[44:45], v3, v226
	v_cmp_le_u32_e64 s[46:47], v3, v246
	v_or_b32_e32 v3, 43, v1
	v_cmp_lt_i32_e64 s[48:49], v3, v226
	v_cmp_gt_u32_e64 s[50:51], v3, v246
	s_or_b64 s[48:49], s[48:49], s[50:51]
	v_or_b32_e32 v3, 16, v0
	v_cndmask_b32_e64 v71, v71, v244, s[48:49]
	v_cmp_ge_i32_e64 s[48:49], v3, v226
	v_cmp_le_u32_e64 s[50:51], v3, v246
	v_or_b32_e32 v3, 48, v0
	v_cmp_lt_i32_e64 s[52:53], v3, v226
	v_cmp_gt_u32_e64 s[54:55], v3, v246
	s_or_b64 s[52:53], s[52:53], s[54:55]
	v_or_b32_e32 v3, 17, v0
	v_cndmask_b32_e64 v72, v72, v244, s[52:53]
	v_cmp_ge_i32_e64 s[52:53], v3, v226
	v_cmp_le_u32_e64 s[54:55], v3, v246
	v_or_b32_e32 v3, 49, v0
	v_cmp_lt_i32_e64 s[56:57], v3, v226
	v_cmp_gt_u32_e64 s[58:59], v3, v246
	s_or_b64 s[56:57], s[56:57], s[58:59]
	v_or_b32_e32 v3, 18, v0
	v_cndmask_b32_e64 v73, v73, v244, s[56:57]
	v_cmp_ge_i32_e64 s[56:57], v3, v226
	v_cmp_le_u32_e64 s[58:59], v3, v246
	v_or_b32_e32 v3, 50, v0
	v_cmp_lt_i32_e64 s[60:61], v3, v226
	v_cmp_gt_u32_e64 s[62:63], v3, v246
	s_or_b64 s[60:61], s[60:61], s[62:63]
	v_or_b32_e32 v3, 19, v1
	v_cndmask_b32_e64 v74, v74, v244, s[60:61]
	v_cmp_ge_i32_e64 s[60:61], v3, v226
	v_cmp_le_u32_e64 s[62:63], v3, v246
	v_or_b32_e32 v3, 51, v1
	v_cmp_lt_i32_e64 s[64:65], v3, v226
	v_cmp_gt_u32_e64 s[66:67], v3, v246
	s_or_b64 s[64:65], s[64:65], s[66:67]
	v_or_b32_e32 v3, 24, v0
	v_cndmask_b32_e64 v75, v75, v244, s[64:65]
	v_cmp_ge_i32_e64 s[64:65], v3, v226
	v_cmp_le_u32_e64 s[66:67], v3, v246
	v_or_b32_e32 v3, 56, v0
	v_cmp_lt_i32_e64 s[68:69], v3, v226
	v_cmp_gt_u32_e64 s[70:71], v3, v246
	s_or_b64 s[68:69], s[68:69], s[70:71]
	v_or_b32_e32 v3, 25, v0
	v_cndmask_b32_e64 v76, v76, v244, s[68:69]
	v_cmp_ge_i32_e64 s[68:69], v3, v226
	v_cmp_le_u32_e64 s[70:71], v3, v246
	v_or_b32_e32 v3, 57, v0
	v_cmp_ge_i32_e32 vcc, v0, v226
	v_cmp_le_u32_e64 s[16:17], v0, v246
	v_cmp_lt_u32_e64 s[20:21], v0, v246
	v_cmp_lt_i32_e64 s[72:73], v3, v226
	v_cmp_gt_u32_e64 s[74:75], v3, v246
	v_or_b32_e32 v3, 26, v0
	v_or_b32_e32 v0, 58, v0
	v_cmp_lt_i32_e64 s[76:77], v0, v226
	v_cmp_gt_u32_e64 s[78:79], v0, v246
	s_or_b64 s[76:77], s[76:77], s[78:79]
	v_or_b32_e32 v0, 27, v1
	v_cndmask_b32_e64 v78, v78, v244, s[76:77]
	v_cmp_ge_i32_e64 s[76:77], v0, v226
	v_cmp_le_u32_e64 s[78:79], v0, v246
	v_or_b32_e32 v0, 59, v1
	s_or_b64 s[72:73], s[72:73], s[74:75]
	v_cmp_lt_i32_e64 s[82:83], v0, v226
	v_cmp_gt_u32_e64 s[84:85], v0, v246
	v_cndmask_b32_e64 v77, v77, v244, s[72:73]
	v_cmp_ge_i32_e64 s[72:73], v3, v226
	v_cmp_le_u32_e64 s[74:75], v3, v246
	s_or_b64 s[82:83], s[82:83], s[84:85]
	s_and_saveexec_b64 s[12:13], s[82:83]
	v_mov_b32_e32 v79, s5
	s_or_b64 exec, exec, s[12:13]
	s_and_b64 vcc, vcc, s[16:17]
	v_cndmask_b32_e32 v80, v244, v80, vcc
	s_and_b64 vcc, s[20:21], s[18:19]
	v_cndmask_b32_e32 v81, v244, v81, vcc
	s_and_b64 vcc, s[22:23], s[24:25]
	v_cndmask_b32_e32 v82, v244, v82, vcc
	s_and_b64 vcc, s[26:27], s[28:29]
	v_cndmask_b32_e32 v83, v244, v83, vcc
	s_and_b64 vcc, s[30:31], s[34:35]
	v_cndmask_b32_e32 v84, v244, v84, vcc
	s_and_b64 vcc, s[36:37], s[38:39]
	v_cndmask_b32_e32 v85, v244, v85, vcc
	s_and_b64 vcc, s[40:41], s[42:43]
	v_cndmask_b32_e32 v86, v244, v86, vcc
	s_and_b64 vcc, s[44:45], s[46:47]
	v_cndmask_b32_e32 v87, v244, v87, vcc
	s_and_b64 vcc, s[48:49], s[50:51]
	v_cndmask_b32_e32 v88, v244, v88, vcc
	s_and_b64 vcc, s[52:53], s[54:55]
	v_cndmask_b32_e32 v89, v244, v89, vcc
	s_and_b64 vcc, s[56:57], s[58:59]
	v_cndmask_b32_e32 v90, v244, v90, vcc
	s_and_b64 vcc, s[60:61], s[62:63]
	v_cndmask_b32_e32 v91, v244, v91, vcc
	s_and_b64 vcc, s[64:65], s[66:67]
	v_cndmask_b32_e32 v92, v244, v92, vcc
	s_and_b64 vcc, s[68:69], s[70:71]
	v_cndmask_b32_e32 v93, v244, v93, vcc
	s_and_b64 vcc, s[72:73], s[74:75]
	v_cndmask_b32_e32 v94, v244, v94, vcc
	s_and_b64 vcc, s[76:77], s[78:79]
	v_cndmask_b32_e32 v95, v244, v95, vcc

.LBB0_1023:
	v_exp_f32_e32 v80, v80
	v_exp_f32_e32 v64, v64
	v_exp_f32_e32 v81, v81
	v_exp_f32_e32 v65, v65
	v_exp_f32_e32 v82, v82
	v_exp_f32_e32 v66, v66
	v_exp_f32_e32 v83, v83
	v_exp_f32_e32 v67, v67
	v_exp_f32_e32 v84, v84
	v_exp_f32_e32 v68, v68
	v_exp_f32_e32 v85, v85
	v_exp_f32_e32 v69, v69
	v_exp_f32_e32 v86, v86
	v_exp_f32_e32 v70, v70
	v_exp_f32_e32 v87, v87
	v_exp_f32_e32 v71, v71
	v_exp_f32_e32 v88, v88
	v_exp_f32_e32 v72, v72
	v_exp_f32_e32 v89, v89
	v_exp_f32_e32 v73, v73
	v_exp_f32_e32 v90, v90
	v_exp_f32_e32 v74, v74
	v_exp_f32_e32 v91, v91
	v_exp_f32_e32 v75, v75
	v_exp_f32_e32 v92, v92
	v_exp_f32_e32 v76, v76
	v_exp_f32_e32 v93, v93
	v_exp_f32_e32 v77, v77
	v_exp_f32_e32 v94, v94
	v_exp_f32_e32 v78, v78
	v_exp_f32_e32 v95, v95
	v_exp_f32_e32 v79, v79
	v_add_f32_e32 v0, v80, v64
	v_add_f32_e32 v1, v81, v65
	v_add_f32_e32 v3, v82, v66
	v_add_f32_e32 v116, v83, v67
	v_cvt_pk_bf16_f32 v80, v80, v81
	v_add_f32_e32 v0, v0, v84
	v_add_f32_e32 v1, v1, v85
	v_add_f32_e32 v3, v3, v86
	v_add_f32_e32 v116, v116, v87
	v_cvt_pk_bf16_f32 v81, v82, v83
	v_add_f32_e32 v0, v0, v68
	v_add_f32_e32 v1, v1, v69
	v_add_f32_e32 v3, v3, v70
	v_add_f32_e32 v116, v116, v71
	v_cvt_pk_bf16_f32 v82, v84, v85
	v_add_f32_e32 v0, v0, v88
	v_add_f32_e32 v1, v1, v89
	v_add_f32_e32 v3, v3, v90
	v_add_f32_e32 v116, v116, v91
	v_cvt_pk_bf16_f32 v83, v86, v87
	v_add_f32_e32 v0, v0, v72
	v_add_f32_e32 v1, v1, v73
	v_add_f32_e32 v3, v3, v74
	v_add_f32_e32 v116, v116, v75
	v_cvt_pk_bf16_f32 v84, v88, v89
	v_add_f32_e32 v0, v0, v92
	v_add_f32_e32 v1, v1, v93
	v_add_f32_e32 v3, v3, v94
	v_add_f32_e32 v116, v116, v95
	v_cvt_pk_bf16_f32 v85, v90, v91
	v_add_f32_e32 v0, v0, v76
	v_add_f32_e32 v1, v1, v77
	v_add_f32_e32 v3, v3, v78
	v_add_f32_e32 v116, v116, v79
	v_cvt_pk_bf16_f32 v86, v92, v93
	v_add_f32_e32 v0, v0, v1
	v_add_f32_e32 v1, v3, v116
	v_cvt_pk_bf16_f32 v87, v94, v95
	v_add_f32_e32 v0, v0, v1
	v_cvt_pk_bf16_f32 v64, v64, v65
	v_cvt_pk_bf16_f32 v65, v66, v67
	v_cvt_pk_bf16_f32 v66, v68, v69
	v_cvt_pk_bf16_f32 v67, v70, v71
	v_cvt_pk_bf16_f32 v68, v72, v73
	v_cvt_pk_bf16_f32 v69, v74, v75
	v_cvt_pk_bf16_f32 v70, v76, v77
	v_cvt_pk_bf16_f32 v71, v78, v79
	v_mfma_f32_32x32x16_bf16 v[32:47], v[4:7], v[80:83], v[32:47]
	s_waitcnt lgkmcnt(12)
	v_mfma_f32_32x32x16_bf16 v[16:31], v[8:11], v[80:83], v[16:31]
	s_waitcnt lgkmcnt(10)
	v_mfma_f32_32x32x16_bf16 v[32:47], v[12:15], v[84:87], v[32:47]
	s_waitcnt lgkmcnt(8)
	v_mfma_f32_32x32x16_bf16 v[16:31], v[96:99], v[84:87], v[16:31]
	s_waitcnt lgkmcnt(6)
	v_mfma_f32_32x32x16_bf16 v[32:47], v[100:103], v[64:67], v[32:47]
	s_waitcnt lgkmcnt(4)
	v_mfma_f32_32x32x16_bf16 v[16:31], v[104:107], v[64:67], v[16:31]
	s_waitcnt lgkmcnt(2)
	v_mfma_f32_32x32x16_bf16 v[32:47], v[108:111], v[68:71], v[32:47]
	s_waitcnt lgkmcnt(0)
	v_mfma_f32_32x32x16_bf16 v[16:31], v[112:115], v[68:71], v[16:31]
	s_andn2_b64 vcc, exec, s[80:81]
	s_mov_b64 s[16:17], -1
	s_cbranch_vccnz .LBB0_996
	s_lshl_b64 s[12:13], 1, s96
	s_andn2_b64 s[12:13], s[86:87], s[12:13]
	s_mov_b64 s[16:17], 0
	s_waitcnt vmcnt(1)
	ds_write_b128 v192, v[148:151]
	s_waitcnt vmcnt(0)
	ds_write_b128 v194, v[152:155] offset:18432
	s_waitcnt lgkmcnt(0)
	s_barrier
	s_branch .LBB0_996

.LBB0_1031:
	s_setprio 0
	s_waitcnt vmcnt(0)
	s_barrier
	s_mov_b64 s[0:1], exec
	v_readlane_b32 s2, v252, 2
	v_readlane_b32 s3, v252, 3
	s_and_b64 s[2:3], s[0:1], s[2:3]
	s_mov_b64 exec, s[2:3]
	s_cbranch_execz .LBB0_1083
	s_add_i32 s2, 0, 0x20040
	v_mov_b32_e32 v0, s2
	s_waitcnt vmcnt(0) expcnt(0) lgkmcnt(0)
	ds_read_b32 v2, v0
	s_add_i32 s2, 0, 0x20044
	v_mov_b32_e32 v0, s2
	ds_read_b32 v0, v0
	s_waitcnt lgkmcnt(1)
	v_cmp_ne_u32_e32 vcc, 0, v2
	s_cbranch_vccnz .LBB0_1047
	s_add_u32 s4, s88, 0x1000
	s_addc_u32 s5, s89, 0
	s_add_u32 s6, s88, 0x1100
	s_addc_u32 s7, s89, 0
	s_add_u32 s8, s88, 0x1200
	v_readlane_b32 s2, v252, 0
	s_addc_u32 s9, s89, 0
	s_mul_i32 s2, s91, s2
	s_add_u32 s10, s88, 0x1300
	s_mul_i32 s2, s2, s90
	s_addc_u32 s11, s89, 0
	s_mov_b32 s3, 1
	v_mov_b32_e32 v16, 0
	s_branch .LBB0_1035
